# EpiRes epilogue: batch the 16 residual bf16 loads into 2 prefetch bursts with counted vmcnt instead of 16 serialized load->vmcnt(0)
# baseline (speedup 1.0000x reference)
.LBB0_303:
	v_lshlrev_b32_e32 v146, 6, v0
	v_mov_b32_e32 v147, s23
	v_add3_u32 v186, v146, s22, v147
	v_lshlrev_b32_e64 v146, 6, s22
	v_add3_u32 v188, v146, v0, s23
	v_cndmask_b32_e64 v170, v186, v188, s[10:11]
	v_ashrrev_i32_e32 v171, 31, v170
	v_lshlrev_b64 v[172:173], 11, v[170:171]
	v_cndmask_b32_e64 v0, 0, 1, s[20:21]
	v_lshl_add_u64 v[146:147], s[78:79], 0, v[172:173]
	v_cmp_gt_i32_e64 s[0:1], s7, v170
	v_cmp_ne_u32_e64 s[14:15], 1, v0
	s_andn2_b64 vcc, exec, s[20:21]
	v_lshl_add_u64 v[168:169], v[166:167], 1, v[146:147]
	s_cbranch_vccnz .LBB0_305
	v_add_u32_e32 v246, 0x0, v186
	v_add_u32_e32 v247, 0x0, v188
	v_cndmask_b32_e64 v246, v246, v247, s[10:11]
	v_ashrrev_i32_e32 v247, 31, v246
	v_lshlrev_b64 v[246:247], 11, v[246:247]
	v_lshl_add_u64 v[246:247], s[78:79], 0, v[246:247]
	v_lshl_add_u64 v[246:247], v[166:167], 1, v[246:247]
	global_load_dwordx4 v[192:195], v[246:247], off
	global_load_dwordx4 v[196:199], v[246:247], off offset:256
	v_add_u32_e32 v246, 0x400, v186
	v_add_u32_e32 v247, 0x10, v188
	v_cndmask_b32_e64 v246, v246, v247, s[10:11]
	v_ashrrev_i32_e32 v247, 31, v246
	v_lshlrev_b64 v[246:247], 11, v[246:247]
	v_lshl_add_u64 v[246:247], s[78:79], 0, v[246:247]
	v_lshl_add_u64 v[246:247], v[166:167], 1, v[246:247]
	global_load_dwordx4 v[218:221], v[246:247], off
	global_load_dwordx4 v[222:225], v[246:247], off offset:256
	v_add_u32_e32 v246, 0x800, v186
	v_add_u32_e32 v247, 0x20, v188
	v_cndmask_b32_e64 v246, v246, v247, s[10:11]
	v_ashrrev_i32_e32 v247, 31, v246
	v_lshlrev_b64 v[246:247], 11, v[246:247]
	v_lshl_add_u64 v[246:247], s[78:79], 0, v[246:247]
	v_lshl_add_u64 v[246:247], v[166:167], 1, v[246:247]
	global_load_dwordx4 v[226:229], v[246:247], off
	global_load_dwordx4 v[230:233], v[246:247], off offset:256
	v_add_u32_e32 v246, 0xc00, v186
	v_add_u32_e32 v247, 0x30, v188
	v_cndmask_b32_e64 v246, v246, v247, s[10:11]
	v_ashrrev_i32_e32 v247, 31, v246
	v_lshlrev_b64 v[246:247], 11, v[246:247]
	v_lshl_add_u64 v[246:247], s[78:79], 0, v[246:247]
	v_lshl_add_u64 v[246:247], v[166:167], 1, v[246:247]
	global_load_dwordx4 v[234:237], v[246:247], off
	global_load_dwordx4 v[238:241], v[246:247], off offset:256
	v_add_u32_e32 v246, 0x2, v186
	v_add_u32_e32 v247, 0x80, v188
	v_cndmask_b32_e64 v246, v246, v247, s[10:11]
	v_ashrrev_i32_e32 v247, 31, v246
	v_lshlrev_b64 v[246:247], 11, v[246:247]
	v_lshl_add_u64 v[246:247], s[78:79], 0, v[246:247]
	v_lshl_add_u64 v[246:247], v[166:167], 1, v[246:247]
	global_load_dwordx4 v[242:245], v[246:247], off
	global_load_dwordx4 v[242:245], v[246:247], off offset:256
	v_add_u32_e32 v246, 0x402, v186
	v_add_u32_e32 v247, 0x90, v188
	v_cndmask_b32_e64 v246, v246, v247, s[10:11]
	v_ashrrev_i32_e32 v247, 31, v246
	v_lshlrev_b64 v[246:247], 11, v[246:247]
	v_lshl_add_u64 v[246:247], s[78:79], 0, v[246:247]
	v_lshl_add_u64 v[246:247], v[166:167], 1, v[246:247]
	global_load_dwordx4 v[242:245], v[246:247], off
	global_load_dwordx4 v[242:245], v[246:247], off offset:256
	v_add_u32_e32 v246, 0x802, v186
	v_add_u32_e32 v247, 0xa0, v188
	v_cndmask_b32_e64 v246, v246, v247, s[10:11]
	v_ashrrev_i32_e32 v247, 31, v246
	v_lshlrev_b64 v[246:247], 11, v[246:247]
	v_lshl_add_u64 v[246:247], s[78:79], 0, v[246:247]
	v_lshl_add_u64 v[246:247], v[166:167], 1, v[246:247]
	global_load_dwordx4 v[242:245], v[246:247], off
	global_load_dwordx4 v[242:245], v[246:247], off offset:256
	v_add_u32_e32 v246, 0xc02, v186
	v_add_u32_e32 v247, 0xb0, v188
	v_cndmask_b32_e64 v246, v246, v247, s[10:11]
	v_ashrrev_i32_e32 v247, 31, v246
	v_lshlrev_b64 v[246:247], 11, v[246:247]
	v_lshl_add_u64 v[246:247], s[78:79], 0, v[246:247]
	v_lshl_add_u64 v[246:247], v[166:167], 1, v[246:247]
	global_load_dwordx4 v[242:245], v[246:247], off
	global_load_dwordx4 v[242:245], v[246:247], off offset:256
	s_waitcnt vmcnt(15)
	s_mov_b64 s[44:45], 0
	v_lshlrev_b32_e32 v150, 16, v192
	v_and_b32_e32 v151, 0xffff0000, v192
	v_lshlrev_b32_e32 v152, 16, v193
	v_and_b32_e32 v153, 0xffff0000, v193
	v_lshlrev_b32_e32 v146, 16, v194
	v_and_b32_e32 v147, 0xffff0000, v194
	v_lshlrev_b32_e32 v148, 16, v195
	v_and_b32_e32 v149, 0xffff0000, v195
	s_branch .LBB0_306

.LBB0_306:
	v_add_u32_e32 v0, 0xffffe000, v170
	s_andn2_b64 vcc, exec, s[44:45]
	v_readlane_b32 s36, v253, 24
	v_lshlrev_b64 v[190:191], 12, v[0:1]
	v_lshlrev_b64 v[174:175], 12, v[170:171]
	v_readlane_b32 s37, v253, 25
	v_readlane_b32 s38, v253, 26
	v_readlane_b32 s39, v253, 27
	v_lshl_add_u64 v[170:171], s[36:37], 0, v[174:175]
	v_readlane_b32 s40, v253, 28
	v_lshl_add_u64 v[190:191], s[38:39], 0, v[190:191]
	v_cndmask_b32_e64 v171, v191, v171, s[0:1]
	v_cndmask_b32_e64 v170, v190, v170, s[0:1]
	v_readlane_b32 s41, v253, 29
	v_readlane_b32 s42, v253, 30
	v_readlane_b32 s43, v253, 31
	v_readlane_b32 s44, v253, 32
	v_readlane_b32 s45, v253, 33
	v_readlane_b32 s46, v253, 34
	v_readlane_b32 s47, v253, 35
	v_readlane_b32 s48, v253, 36
	v_readlane_b32 s49, v253, 37
	v_readlane_b32 s50, v253, 38
	v_readlane_b32 s51, v253, 39
	s_cbranch_vccnz .LBB0_308
	v_lshl_add_u64 v[150:151], v[166:167], 2, v[170:171]
	global_load_dwordx4 v[146:149], v[150:151], off offset:16
	s_nop 0
	global_load_dwordx4 v[150:153], v[150:151], off
	s_waitcnt vmcnt(0)
.LBB0_308:
	v_pk_fma_f32 v[138:139], v[138:139], v[78:79], v[146:147]
	v_cndmask_b32_e64 v0, 0, 1, s[92:93]
	v_lshl_add_u64 v[146:147], s[54:55], 0, v[172:173]
	v_pk_fma_f32 v[144:145], v[144:145], v[76:77], v[152:153]
	v_pk_fma_f32 v[142:143], v[142:143], v[74:75], v[150:151]
	v_pk_fma_f32 v[140:141], v[140:141], v[80:81], v[148:149]
	v_cmp_ne_u32_e64 s[16:17], 1, v0
	s_andn2_b64 vcc, exec, s[92:93]
	v_lshl_add_u64 v[146:147], v[166:167], 1, v[146:147]
	s_cbranch_vccnz .LBB0_310
	v_cvt_pk_bf16_f32 v148, v142, v143
	v_cvt_pk_bf16_f32 v149, v144, v145
	v_cvt_pk_bf16_f32 v150, v138, v139
	v_cvt_pk_bf16_f32 v151, v140, v141
	global_store_dwordx4 v[146:147], v[148:151], off

.LBB0_312:
	s_and_b64 vcc, exec, s[14:15]
	s_cbranch_vccnz .LBB0_321
	s_waitcnt vmcnt(15)
	v_lshlrev_b32_e32 v142, 16, v196
	v_and_b32_e32 v143, 0xffff0000, v196
	v_lshlrev_b32_e32 v144, 16, v197
	v_and_b32_e32 v145, 0xffff0000, v197
	v_lshlrev_b32_e32 v138, 16, v198
	v_and_b32_e32 v139, 0xffff0000, v198
	v_lshlrev_b32_e32 v140, 16, v199
	v_and_b32_e32 v141, 0xffff0000, v199
	s_cbranch_execnz .LBB0_315
.LBB0_314:
	v_lshl_add_u64 v[142:143], v[166:167], 2, v[170:171]
	global_load_dwordx4 v[138:141], v[142:143], off offset:528
	s_nop 0
	global_load_dwordx4 v[142:145], v[142:143], off offset:512
	s_waitcnt vmcnt(0)
.LBB0_315:
	v_pk_fma_f32 v[136:137], v[136:137], v[64:65], v[144:145]
	v_pk_fma_f32 v[134:135], v[134:135], v[62:63], v[142:143]
	v_pk_fma_f32 v[132:133], v[132:133], v[68:69], v[140:141]
	s_and_b64 vcc, exec, s[16:17]
	v_pk_fma_f32 v[130:131], v[130:131], v[66:67], v[138:139]
	s_cbranch_vccnz .LBB0_317
	v_cvt_pk_bf16_f32 v138, v134, v135
	v_cvt_pk_bf16_f32 v139, v136, v137
	v_cvt_pk_bf16_f32 v140, v130, v131
	v_cvt_pk_bf16_f32 v141, v132, v133
	global_store_dwordx4 v[146:147], v[138:141], off offset:256

.LBB0_319:
	v_add_u32_e32 v0, 0x400, v186
	s_nop 0
	v_add_u32_e32 v130, 16, v188
	v_cndmask_b32_e64 v140, v0, v130, s[10:11]
	v_ashrrev_i32_e32 v141, 31, v140
	v_lshlrev_b64 v[142:143], 11, v[140:141]
	v_lshl_add_u64 v[130:131], s[78:79], 0, v[142:143]
	v_cmp_gt_i32_e64 s[0:1], s7, v140
	s_and_b64 vcc, exec, s[14:15]
	v_lshl_add_u64 v[138:139], v[166:167], 1, v[130:131]
	s_cbranch_vccnz .LBB0_322
	s_waitcnt vmcnt(15)
	s_mov_b64 vcc, 0
	v_lshlrev_b32_e32 v134, 16, v218
	v_and_b32_e32 v135, 0xffff0000, v218
	v_lshlrev_b32_e32 v136, 16, v219
	v_and_b32_e32 v137, 0xffff0000, v219
	v_lshlrev_b32_e32 v130, 16, v220
	v_and_b32_e32 v131, 0xffff0000, v220
	v_lshlrev_b32_e32 v132, 16, v221
	v_and_b32_e32 v133, 0xffff0000, v221
	s_branch .LBB0_323

.LBB0_323:
	v_add_u32_e32 v0, 0xffffe000, v140
	v_readlane_b32 s36, v253, 24
	v_lshlrev_b64 v[146:147], 12, v[0:1]
	v_lshlrev_b64 v[144:145], 12, v[140:141]
	v_readlane_b32 s37, v253, 25
	v_readlane_b32 s38, v253, 26
	v_readlane_b32 s39, v253, 27
	v_lshl_add_u64 v[140:141], s[36:37], 0, v[144:145]
	s_andn2_b64 vcc, exec, vcc
	v_lshl_add_u64 v[146:147], s[38:39], 0, v[146:147]
	v_cndmask_b32_e64 v141, v147, v141, s[0:1]
	v_cndmask_b32_e64 v140, v146, v140, s[0:1]
	v_readlane_b32 s40, v253, 28
	v_readlane_b32 s41, v253, 29
	v_readlane_b32 s42, v253, 30
	v_readlane_b32 s43, v253, 31
	v_readlane_b32 s44, v253, 32
	v_readlane_b32 s45, v253, 33
	v_readlane_b32 s46, v253, 34
	v_readlane_b32 s47, v253, 35
	v_readlane_b32 s48, v253, 36
	v_readlane_b32 s49, v253, 37
	v_readlane_b32 s50, v253, 38
	v_readlane_b32 s51, v253, 39
	s_cbranch_vccnz .LBB0_325
	v_lshl_add_u64 v[134:135], v[166:167], 2, v[140:141]
	global_load_dwordx4 v[130:133], v[134:135], off offset:16
	s_nop 0
	global_load_dwordx4 v[134:137], v[134:135], off
	s_waitcnt vmcnt(0)
.LBB0_325:
	v_pk_fma_f32 v[122:123], v[122:123], v[78:79], v[130:131]
	v_lshl_add_u64 v[130:131], s[54:55], 0, v[142:143]
	v_pk_fma_f32 v[128:129], v[128:129], v[76:77], v[136:137]
	v_pk_fma_f32 v[126:127], v[126:127], v[74:75], v[134:135]
	v_pk_fma_f32 v[124:125], v[124:125], v[80:81], v[132:133]
	s_and_b64 vcc, exec, s[16:17]
	v_lshl_add_u64 v[130:131], v[166:167], 1, v[130:131]
	s_cbranch_vccnz .LBB0_327
	v_cvt_pk_bf16_f32 v132, v126, v127
	v_cvt_pk_bf16_f32 v133, v128, v129
	v_cvt_pk_bf16_f32 v134, v122, v123
	v_cvt_pk_bf16_f32 v135, v124, v125
	global_store_dwordx4 v[130:131], v[132:135], off

.LBB0_329:
	s_and_b64 vcc, exec, s[14:15]
	s_cbranch_vccnz .LBB0_338
	s_waitcnt vmcnt(15)
	v_lshlrev_b32_e32 v126, 16, v222
	v_and_b32_e32 v127, 0xffff0000, v222
	v_lshlrev_b32_e32 v128, 16, v223
	v_and_b32_e32 v129, 0xffff0000, v223
	v_lshlrev_b32_e32 v122, 16, v224
	v_and_b32_e32 v123, 0xffff0000, v224
	v_lshlrev_b32_e32 v124, 16, v225
	v_and_b32_e32 v125, 0xffff0000, v225
	s_cbranch_execnz .LBB0_332
.LBB0_331:
	v_lshl_add_u64 v[126:127], v[166:167], 2, v[140:141]
	global_load_dwordx4 v[122:125], v[126:127], off offset:528
	s_nop 0
	global_load_dwordx4 v[126:129], v[126:127], off offset:512
	s_waitcnt vmcnt(0)
.LBB0_332:
	v_pk_fma_f32 v[120:121], v[120:121], v[64:65], v[128:129]
	v_pk_fma_f32 v[118:119], v[118:119], v[62:63], v[126:127]
	v_pk_fma_f32 v[116:117], v[116:117], v[68:69], v[124:125]
	s_and_b64 vcc, exec, s[16:17]
	v_pk_fma_f32 v[114:115], v[114:115], v[66:67], v[122:123]
	s_cbranch_vccnz .LBB0_334
	v_cvt_pk_bf16_f32 v122, v118, v119
	v_cvt_pk_bf16_f32 v123, v120, v121
	v_cvt_pk_bf16_f32 v124, v114, v115
	v_cvt_pk_bf16_f32 v125, v116, v117
	global_store_dwordx4 v[130:131], v[122:125], off offset:256

.LBB0_336:
	v_add_u32_e32 v0, 0x800, v186
	s_nop 0
	v_add_u32_e32 v114, 32, v188
	v_cndmask_b32_e64 v124, v0, v114, s[10:11]
	v_ashrrev_i32_e32 v125, 31, v124
	v_lshlrev_b64 v[126:127], 11, v[124:125]
	v_lshl_add_u64 v[114:115], s[78:79], 0, v[126:127]
	v_cmp_gt_i32_e64 s[0:1], s7, v124
	s_and_b64 vcc, exec, s[14:15]
	v_lshl_add_u64 v[122:123], v[166:167], 1, v[114:115]
	s_cbranch_vccnz .LBB0_339
	s_waitcnt vmcnt(15)
	s_mov_b64 vcc, 0
	v_lshlrev_b32_e32 v118, 16, v226
	v_and_b32_e32 v119, 0xffff0000, v226
	v_lshlrev_b32_e32 v120, 16, v227
	v_and_b32_e32 v121, 0xffff0000, v227
	v_lshlrev_b32_e32 v114, 16, v228
	v_and_b32_e32 v115, 0xffff0000, v228
	v_lshlrev_b32_e32 v116, 16, v229
	v_and_b32_e32 v117, 0xffff0000, v229
	s_branch .LBB0_340

.LBB0_340:
	v_add_u32_e32 v0, 0xffffe000, v124
	v_readlane_b32 s36, v253, 24
	v_lshlrev_b64 v[130:131], 12, v[0:1]
	v_lshlrev_b64 v[128:129], 12, v[124:125]
	v_readlane_b32 s37, v253, 25
	v_readlane_b32 s38, v253, 26
	v_readlane_b32 s39, v253, 27
	v_lshl_add_u64 v[124:125], s[36:37], 0, v[128:129]
	s_andn2_b64 vcc, exec, vcc
	v_lshl_add_u64 v[130:131], s[38:39], 0, v[130:131]
	v_cndmask_b32_e64 v125, v131, v125, s[0:1]
	v_cndmask_b32_e64 v124, v130, v124, s[0:1]
	v_readlane_b32 s40, v253, 28
	v_readlane_b32 s41, v253, 29
	v_readlane_b32 s42, v253, 30
	v_readlane_b32 s43, v253, 31
	v_readlane_b32 s44, v253, 32
	v_readlane_b32 s45, v253, 33
	v_readlane_b32 s46, v253, 34
	v_readlane_b32 s47, v253, 35
	v_readlane_b32 s48, v253, 36
	v_readlane_b32 s49, v253, 37
	v_readlane_b32 s50, v253, 38
	v_readlane_b32 s51, v253, 39
	s_cbranch_vccnz .LBB0_342
	v_lshl_add_u64 v[118:119], v[166:167], 2, v[124:125]
	global_load_dwordx4 v[114:117], v[118:119], off offset:16
	s_nop 0
	global_load_dwordx4 v[118:121], v[118:119], off
	s_waitcnt vmcnt(0)
.LBB0_342:
	v_pk_fma_f32 v[106:107], v[106:107], v[78:79], v[114:115]
	v_lshl_add_u64 v[114:115], s[54:55], 0, v[126:127]
	v_pk_fma_f32 v[112:113], v[112:113], v[76:77], v[120:121]
	v_pk_fma_f32 v[110:111], v[110:111], v[74:75], v[118:119]
	v_pk_fma_f32 v[108:109], v[108:109], v[80:81], v[116:117]
	s_and_b64 vcc, exec, s[16:17]
	v_lshl_add_u64 v[114:115], v[166:167], 1, v[114:115]
	s_cbranch_vccnz .LBB0_344
	v_cvt_pk_bf16_f32 v116, v110, v111
	v_cvt_pk_bf16_f32 v117, v112, v113
	v_cvt_pk_bf16_f32 v118, v106, v107
	v_cvt_pk_bf16_f32 v119, v108, v109
	global_store_dwordx4 v[114:115], v[116:119], off

.LBB0_346:
	s_and_b64 vcc, exec, s[14:15]
	s_cbranch_vccnz .LBB0_355
	s_waitcnt vmcnt(15)
	v_lshlrev_b32_e32 v110, 16, v230
	v_and_b32_e32 v111, 0xffff0000, v230
	v_lshlrev_b32_e32 v112, 16, v231
	v_and_b32_e32 v113, 0xffff0000, v231
	v_lshlrev_b32_e32 v106, 16, v232
	v_and_b32_e32 v107, 0xffff0000, v232
	v_lshlrev_b32_e32 v108, 16, v233
	v_and_b32_e32 v109, 0xffff0000, v233
	s_cbranch_execnz .LBB0_349
.LBB0_348:
	v_lshl_add_u64 v[110:111], v[166:167], 2, v[124:125]
	global_load_dwordx4 v[106:109], v[110:111], off offset:528
	s_nop 0
	global_load_dwordx4 v[110:113], v[110:111], off offset:512
	s_waitcnt vmcnt(0)
.LBB0_349:
	v_pk_fma_f32 v[104:105], v[104:105], v[64:65], v[112:113]
	v_pk_fma_f32 v[102:103], v[102:103], v[62:63], v[110:111]
	v_pk_fma_f32 v[100:101], v[100:101], v[68:69], v[108:109]
	s_and_b64 vcc, exec, s[16:17]
	v_pk_fma_f32 v[98:99], v[98:99], v[66:67], v[106:107]
	s_cbranch_vccnz .LBB0_351
	v_cvt_pk_bf16_f32 v106, v102, v103
	v_cvt_pk_bf16_f32 v107, v104, v105
	v_cvt_pk_bf16_f32 v108, v98, v99
	v_cvt_pk_bf16_f32 v109, v100, v101
	global_store_dwordx4 v[114:115], v[106:109], off offset:256

.LBB0_353:
	v_add_u32_e32 v0, 0xc00, v186
	s_nop 0
	v_add_u32_e32 v98, 48, v188
	v_cndmask_b32_e64 v108, v0, v98, s[10:11]
	v_ashrrev_i32_e32 v109, 31, v108
	v_lshlrev_b64 v[110:111], 11, v[108:109]
	v_lshl_add_u64 v[98:99], s[78:79], 0, v[110:111]
	v_cmp_gt_i32_e64 s[0:1], s7, v108
	s_and_b64 vcc, exec, s[14:15]
	v_lshl_add_u64 v[106:107], v[166:167], 1, v[98:99]
	s_cbranch_vccnz .LBB0_356
	s_waitcnt vmcnt(15)
	s_mov_b64 vcc, 0
	v_lshlrev_b32_e32 v102, 16, v234
	v_and_b32_e32 v103, 0xffff0000, v234
	v_lshlrev_b32_e32 v104, 16, v235
	v_and_b32_e32 v105, 0xffff0000, v235
	v_lshlrev_b32_e32 v98, 16, v236
	v_and_b32_e32 v99, 0xffff0000, v236
	v_lshlrev_b32_e32 v100, 16, v237
	v_and_b32_e32 v101, 0xffff0000, v237
	s_branch .LBB0_357

.LBB0_357:
	v_add_u32_e32 v0, 0xffffe000, v108
	v_readlane_b32 s36, v253, 24
	v_lshlrev_b64 v[114:115], 12, v[0:1]
	v_lshlrev_b64 v[112:113], 12, v[108:109]
	v_readlane_b32 s37, v253, 25
	v_readlane_b32 s38, v253, 26
	v_readlane_b32 s39, v253, 27
	v_lshl_add_u64 v[108:109], s[36:37], 0, v[112:113]
	s_andn2_b64 vcc, exec, vcc
	v_lshl_add_u64 v[114:115], s[38:39], 0, v[114:115]
	v_cndmask_b32_e64 v109, v115, v109, s[0:1]
	v_cndmask_b32_e64 v108, v114, v108, s[0:1]
	v_readlane_b32 s40, v253, 28
	v_readlane_b32 s41, v253, 29
	v_readlane_b32 s42, v253, 30
	v_readlane_b32 s43, v253, 31
	v_readlane_b32 s44, v253, 32
	v_readlane_b32 s45, v253, 33
	v_readlane_b32 s46, v253, 34
	v_readlane_b32 s47, v253, 35
	v_readlane_b32 s48, v253, 36
	v_readlane_b32 s49, v253, 37
	v_readlane_b32 s50, v253, 38
	v_readlane_b32 s51, v253, 39
	s_cbranch_vccnz .LBB0_359
	v_lshl_add_u64 v[102:103], v[166:167], 2, v[108:109]
	global_load_dwordx4 v[98:101], v[102:103], off offset:16
	s_nop 0
	global_load_dwordx4 v[102:105], v[102:103], off
	s_waitcnt vmcnt(0)
.LBB0_359:
	v_pk_fma_f32 v[90:91], v[90:91], v[78:79], v[98:99]
	v_lshl_add_u64 v[98:99], s[54:55], 0, v[110:111]
	v_pk_fma_f32 v[96:97], v[96:97], v[76:77], v[104:105]
	v_pk_fma_f32 v[94:95], v[94:95], v[74:75], v[102:103]
	v_pk_fma_f32 v[92:93], v[92:93], v[80:81], v[100:101]
	s_and_b64 vcc, exec, s[16:17]
	v_lshl_add_u64 v[98:99], v[166:167], 1, v[98:99]
	s_cbranch_vccnz .LBB0_361
	v_cvt_pk_bf16_f32 v100, v94, v95
	v_cvt_pk_bf16_f32 v101, v96, v97
	v_cvt_pk_bf16_f32 v102, v90, v91
	v_cvt_pk_bf16_f32 v103, v92, v93
	global_store_dwordx4 v[98:99], v[100:103], off

.LBB0_363:
	s_and_b64 vcc, exec, s[14:15]
	s_cbranch_vccnz .LBB0_372
	s_waitcnt vmcnt(15)
	v_lshlrev_b32_e32 v94, 16, v238
	v_and_b32_e32 v95, 0xffff0000, v238
	v_lshlrev_b32_e32 v96, 16, v239
	v_and_b32_e32 v97, 0xffff0000, v239
	v_lshlrev_b32_e32 v90, 16, v240
	v_and_b32_e32 v91, 0xffff0000, v240
	v_lshlrev_b32_e32 v92, 16, v241
	v_and_b32_e32 v93, 0xffff0000, v241
	v_add_u32_e32 v246, 0x2, v186
	v_add_u32_e32 v247, 0x80, v188
	v_cndmask_b32_e64 v246, v246, v247, s[10:11]
	v_ashrrev_i32_e32 v247, 31, v246
	v_lshlrev_b64 v[246:247], 11, v[246:247]
	v_lshl_add_u64 v[246:247], s[78:79], 0, v[246:247]
	v_lshl_add_u64 v[246:247], v[166:167], 1, v[246:247]
	global_load_dwordx4 v[192:195], v[246:247], off
	global_load_dwordx4 v[196:199], v[246:247], off offset:256
	v_add_u32_e32 v246, 0x402, v186
	v_add_u32_e32 v247, 0x90, v188
	v_cndmask_b32_e64 v246, v246, v247, s[10:11]
	v_ashrrev_i32_e32 v247, 31, v246
	v_lshlrev_b64 v[246:247], 11, v[246:247]
	v_lshl_add_u64 v[246:247], s[78:79], 0, v[246:247]
	v_lshl_add_u64 v[246:247], v[166:167], 1, v[246:247]
	global_load_dwordx4 v[218:221], v[246:247], off
	global_load_dwordx4 v[222:225], v[246:247], off offset:256
	v_add_u32_e32 v246, 0x802, v186
	v_add_u32_e32 v247, 0xa0, v188
	v_cndmask_b32_e64 v246, v246, v247, s[10:11]
	v_ashrrev_i32_e32 v247, 31, v246
	v_lshlrev_b64 v[246:247], 11, v[246:247]
	v_lshl_add_u64 v[246:247], s[78:79], 0, v[246:247]
	v_lshl_add_u64 v[246:247], v[166:167], 1, v[246:247]
	global_load_dwordx4 v[226:229], v[246:247], off
	global_load_dwordx4 v[230:233], v[246:247], off offset:256
	v_add_u32_e32 v246, 0xc02, v186
	v_add_u32_e32 v247, 0xb0, v188
	v_cndmask_b32_e64 v246, v246, v247, s[10:11]
	v_ashrrev_i32_e32 v247, 31, v246
	v_lshlrev_b64 v[246:247], 11, v[246:247]
	v_lshl_add_u64 v[246:247], s[78:79], 0, v[246:247]
	v_lshl_add_u64 v[246:247], v[166:167], 1, v[246:247]
	global_load_dwordx4 v[234:237], v[246:247], off
	global_load_dwordx4 v[238:241], v[246:247], off offset:256
	s_cbranch_execnz .LBB0_366
.LBB0_365:
	v_lshl_add_u64 v[94:95], v[166:167], 2, v[108:109]
	global_load_dwordx4 v[90:93], v[94:95], off offset:528
	s_nop 0
	global_load_dwordx4 v[94:97], v[94:95], off offset:512
	s_waitcnt vmcnt(0)
.LBB0_366:
	v_pk_fma_f32 v[88:89], v[88:89], v[64:65], v[96:97]
	v_pk_fma_f32 v[86:87], v[86:87], v[62:63], v[94:95]
	v_pk_fma_f32 v[84:85], v[84:85], v[68:69], v[92:93]
	s_and_b64 vcc, exec, s[16:17]
	v_pk_fma_f32 v[82:83], v[82:83], v[66:67], v[90:91]
	s_cbranch_vccnz .LBB0_368
	v_cvt_pk_bf16_f32 v90, v86, v87
	v_cvt_pk_bf16_f32 v91, v88, v89
	v_cvt_pk_bf16_f32 v92, v82, v83
	v_cvt_pk_bf16_f32 v93, v84, v85
	global_store_dwordx4 v[98:99], v[90:93], off offset:256

.LBB0_370:
	v_add_u32_e32 v0, 2, v186
	s_nop 0
	v_add_u32_e32 v82, 0x80, v188
	v_cndmask_b32_e64 v92, v0, v82, s[10:11]
	v_ashrrev_i32_e32 v93, 31, v92
	v_lshlrev_b64 v[94:95], 11, v[92:93]
	v_lshl_add_u64 v[82:83], s[78:79], 0, v[94:95]
	v_cmp_gt_i32_e64 s[0:1], s7, v92
	s_and_b64 vcc, exec, s[14:15]
	v_lshl_add_u64 v[90:91], v[166:167], 1, v[82:83]
	s_cbranch_vccnz .LBB0_373
	s_waitcnt vmcnt(8)
	s_mov_b64 vcc, 0
	v_lshlrev_b32_e32 v86, 16, v192
	v_and_b32_e32 v87, 0xffff0000, v192
	v_lshlrev_b32_e32 v88, 16, v193
	v_and_b32_e32 v89, 0xffff0000, v193
	v_lshlrev_b32_e32 v82, 16, v194
	v_and_b32_e32 v83, 0xffff0000, v194
	v_lshlrev_b32_e32 v84, 16, v195
	v_and_b32_e32 v85, 0xffff0000, v195
	s_branch .LBB0_374

.LBB0_374:
	v_add_u32_e32 v0, 0xffffe000, v92
	v_readlane_b32 s36, v253, 24
	v_lshlrev_b64 v[98:99], 12, v[0:1]
	v_lshlrev_b64 v[96:97], 12, v[92:93]
	v_readlane_b32 s37, v253, 25
	v_readlane_b32 s38, v253, 26
	v_readlane_b32 s39, v253, 27
	v_lshl_add_u64 v[92:93], s[36:37], 0, v[96:97]
	s_andn2_b64 vcc, exec, vcc
	v_lshl_add_u64 v[98:99], s[38:39], 0, v[98:99]
	v_cndmask_b32_e64 v93, v99, v93, s[0:1]
	v_cndmask_b32_e64 v92, v98, v92, s[0:1]
	v_readlane_b32 s40, v253, 28
	v_readlane_b32 s41, v253, 29
	v_readlane_b32 s42, v253, 30
	v_readlane_b32 s43, v253, 31
	v_readlane_b32 s44, v253, 32
	v_readlane_b32 s45, v253, 33
	v_readlane_b32 s46, v253, 34
	v_readlane_b32 s47, v253, 35
	v_readlane_b32 s48, v253, 36
	v_readlane_b32 s49, v253, 37
	v_readlane_b32 s50, v253, 38
	v_readlane_b32 s51, v253, 39
	s_cbranch_vccnz .LBB0_376
	v_lshl_add_u64 v[86:87], v[166:167], 2, v[92:93]
	global_load_dwordx4 v[82:85], v[86:87], off offset:16
	s_nop 0
	global_load_dwordx4 v[86:89], v[86:87], off
	s_waitcnt vmcnt(0)
.LBB0_376:
	v_pk_fma_f32 v[58:59], v[58:59], v[78:79], v[82:83]
	v_lshl_add_u64 v[82:83], s[54:55], 0, v[94:95]
	v_pk_fma_f32 v[72:73], v[72:73], v[76:77], v[88:89]
	v_pk_fma_f32 v[70:71], v[70:71], v[74:75], v[86:87]
	v_pk_fma_f32 v[60:61], v[60:61], v[80:81], v[84:85]
	s_and_b64 vcc, exec, s[16:17]
	v_lshl_add_u64 v[82:83], v[166:167], 1, v[82:83]
	s_cbranch_vccnz .LBB0_378
	v_cvt_pk_bf16_f32 v84, v70, v71
	v_cvt_pk_bf16_f32 v85, v72, v73
	v_cvt_pk_bf16_f32 v86, v58, v59
	v_cvt_pk_bf16_f32 v87, v60, v61
	global_store_dwordx4 v[82:83], v[84:87], off

.LBB0_380:
	s_and_b64 vcc, exec, s[14:15]
	s_cbranch_vccnz .LBB0_389
	s_waitcnt vmcnt(8)
	v_lshlrev_b32_e32 v70, 16, v196
	v_and_b32_e32 v71, 0xffff0000, v196
	v_lshlrev_b32_e32 v72, 16, v197
	v_and_b32_e32 v73, 0xffff0000, v197
	v_lshlrev_b32_e32 v58, 16, v198
	v_and_b32_e32 v59, 0xffff0000, v198
	v_lshlrev_b32_e32 v60, 16, v199
	v_and_b32_e32 v61, 0xffff0000, v199
	s_cbranch_execnz .LBB0_383
.LBB0_382:
	v_lshl_add_u64 v[70:71], v[166:167], 2, v[92:93]
	global_load_dwordx4 v[58:61], v[70:71], off offset:528
	s_nop 0
	global_load_dwordx4 v[70:73], v[70:71], off offset:512
	s_waitcnt vmcnt(0)
.LBB0_383:
	v_pk_fma_f32 v[56:57], v[56:57], v[64:65], v[72:73]
	v_pk_fma_f32 v[54:55], v[54:55], v[62:63], v[70:71]
	v_pk_fma_f32 v[52:53], v[52:53], v[68:69], v[60:61]
	s_and_b64 vcc, exec, s[16:17]
	v_pk_fma_f32 v[50:51], v[50:51], v[66:67], v[58:59]
	s_cbranch_vccnz .LBB0_385
	v_cvt_pk_bf16_f32 v58, v54, v55
	v_cvt_pk_bf16_f32 v59, v56, v57
	v_cvt_pk_bf16_f32 v60, v50, v51
	v_cvt_pk_bf16_f32 v61, v52, v53
	global_store_dwordx4 v[82:83], v[58:61], off offset:256

.LBB0_387:
	v_add_u32_e32 v0, 0x402, v186
	s_nop 0
	v_add_u32_e32 v50, 0x90, v188
	v_cndmask_b32_e64 v60, v0, v50, s[10:11]
	v_ashrrev_i32_e32 v61, 31, v60
	v_lshlrev_b64 v[70:71], 11, v[60:61]
	v_lshl_add_u64 v[50:51], s[78:79], 0, v[70:71]
	v_cmp_gt_i32_e64 s[0:1], s7, v60
	s_and_b64 vcc, exec, s[14:15]
	v_lshl_add_u64 v[58:59], v[166:167], 1, v[50:51]
	s_cbranch_vccnz .LBB0_390
	s_waitcnt vmcnt(8)
	s_mov_b64 vcc, 0
	v_lshlrev_b32_e32 v54, 16, v218
	v_and_b32_e32 v55, 0xffff0000, v218
	v_lshlrev_b32_e32 v56, 16, v219
	v_and_b32_e32 v57, 0xffff0000, v219
	v_lshlrev_b32_e32 v50, 16, v220
	v_and_b32_e32 v51, 0xffff0000, v220
	v_lshlrev_b32_e32 v52, 16, v221
	v_and_b32_e32 v53, 0xffff0000, v221
	s_branch .LBB0_391

.LBB0_391:
	v_add_u32_e32 v0, 0xffffe000, v60
	v_readlane_b32 s36, v253, 24
	v_lshlrev_b64 v[82:83], 12, v[0:1]
	v_lshlrev_b64 v[72:73], 12, v[60:61]
	v_readlane_b32 s37, v253, 25
	v_readlane_b32 s38, v253, 26
	v_readlane_b32 s39, v253, 27
	v_lshl_add_u64 v[60:61], s[36:37], 0, v[72:73]
	s_andn2_b64 vcc, exec, vcc
	v_lshl_add_u64 v[82:83], s[38:39], 0, v[82:83]
	v_cndmask_b32_e64 v61, v83, v61, s[0:1]
	v_cndmask_b32_e64 v60, v82, v60, s[0:1]
	v_readlane_b32 s40, v253, 28
	v_readlane_b32 s41, v253, 29
	v_readlane_b32 s42, v253, 30
	v_readlane_b32 s43, v253, 31
	v_readlane_b32 s44, v253, 32
	v_readlane_b32 s45, v253, 33
	v_readlane_b32 s46, v253, 34
	v_readlane_b32 s47, v253, 35
	v_readlane_b32 s48, v253, 36
	v_readlane_b32 s49, v253, 37
	v_readlane_b32 s50, v253, 38
	v_readlane_b32 s51, v253, 39
	s_cbranch_vccnz .LBB0_393
	v_lshl_add_u64 v[54:55], v[166:167], 2, v[60:61]
	global_load_dwordx4 v[50:53], v[54:55], off offset:16
	s_nop 0
	global_load_dwordx4 v[54:57], v[54:55], off
	s_waitcnt vmcnt(0)
.LBB0_393:
	v_pk_fma_f32 v[42:43], v[42:43], v[78:79], v[50:51]
	v_lshl_add_u64 v[50:51], s[54:55], 0, v[70:71]
	v_pk_fma_f32 v[48:49], v[48:49], v[76:77], v[56:57]
	v_pk_fma_f32 v[46:47], v[46:47], v[74:75], v[54:55]
	v_pk_fma_f32 v[44:45], v[44:45], v[80:81], v[52:53]
	s_and_b64 vcc, exec, s[16:17]
	v_lshl_add_u64 v[50:51], v[166:167], 1, v[50:51]
	s_cbranch_vccnz .LBB0_395
	v_cvt_pk_bf16_f32 v52, v46, v47
	v_cvt_pk_bf16_f32 v53, v48, v49
	v_cvt_pk_bf16_f32 v54, v42, v43
	v_cvt_pk_bf16_f32 v55, v44, v45
	global_store_dwordx4 v[50:51], v[52:55], off

.LBB0_397:
	s_and_b64 vcc, exec, s[14:15]
	s_cbranch_vccnz .LBB0_406
	s_waitcnt vmcnt(8)
	v_lshlrev_b32_e32 v46, 16, v222
	v_and_b32_e32 v47, 0xffff0000, v222
	v_lshlrev_b32_e32 v48, 16, v223
	v_and_b32_e32 v49, 0xffff0000, v223
	v_lshlrev_b32_e32 v42, 16, v224
	v_and_b32_e32 v43, 0xffff0000, v224
	v_lshlrev_b32_e32 v44, 16, v225
	v_and_b32_e32 v45, 0xffff0000, v225
	s_cbranch_execnz .LBB0_400
.LBB0_399:
	v_lshl_add_u64 v[46:47], v[166:167], 2, v[60:61]
	global_load_dwordx4 v[42:45], v[46:47], off offset:528
	s_nop 0
	global_load_dwordx4 v[46:49], v[46:47], off offset:512
	s_waitcnt vmcnt(0)
.LBB0_400:
	v_pk_fma_f32 v[40:41], v[40:41], v[64:65], v[48:49]
	v_pk_fma_f32 v[38:39], v[38:39], v[62:63], v[46:47]
	v_pk_fma_f32 v[36:37], v[36:37], v[68:69], v[44:45]
	s_and_b64 vcc, exec, s[16:17]
	v_pk_fma_f32 v[34:35], v[34:35], v[66:67], v[42:43]
	s_cbranch_vccnz .LBB0_402
	v_cvt_pk_bf16_f32 v42, v38, v39
	v_cvt_pk_bf16_f32 v43, v40, v41
	v_cvt_pk_bf16_f32 v44, v34, v35
	v_cvt_pk_bf16_f32 v45, v36, v37
	global_store_dwordx4 v[50:51], v[42:45], off offset:256

.LBB0_404:
	v_add_u32_e32 v0, 0x802, v186
	s_nop 0
	v_add_u32_e32 v34, 0xa0, v188
	v_cndmask_b32_e64 v44, v0, v34, s[10:11]
	v_ashrrev_i32_e32 v45, 31, v44
	v_lshlrev_b64 v[46:47], 11, v[44:45]
	v_lshl_add_u64 v[34:35], s[78:79], 0, v[46:47]
	v_cmp_gt_i32_e64 s[0:1], s7, v44
	s_and_b64 vcc, exec, s[14:15]
	v_lshl_add_u64 v[42:43], v[166:167], 1, v[34:35]
	s_cbranch_vccnz .LBB0_407
	s_waitcnt vmcnt(8)
	s_mov_b64 vcc, 0
	v_lshlrev_b32_e32 v38, 16, v226
	v_and_b32_e32 v39, 0xffff0000, v226
	v_lshlrev_b32_e32 v40, 16, v227
	v_and_b32_e32 v41, 0xffff0000, v227
	v_lshlrev_b32_e32 v34, 16, v228
	v_and_b32_e32 v35, 0xffff0000, v228
	v_lshlrev_b32_e32 v36, 16, v229
	v_and_b32_e32 v37, 0xffff0000, v229
	s_branch .LBB0_408

.LBB0_408:
	v_add_u32_e32 v0, 0xffffe000, v44
	v_readlane_b32 s36, v253, 24
	v_lshlrev_b64 v[50:51], 12, v[0:1]
	v_lshlrev_b64 v[48:49], 12, v[44:45]
	v_readlane_b32 s37, v253, 25
	v_readlane_b32 s38, v253, 26
	v_readlane_b32 s39, v253, 27
	v_lshl_add_u64 v[44:45], s[36:37], 0, v[48:49]
	s_andn2_b64 vcc, exec, vcc
	v_lshl_add_u64 v[50:51], s[38:39], 0, v[50:51]
	v_cndmask_b32_e64 v45, v51, v45, s[0:1]
	v_cndmask_b32_e64 v44, v50, v44, s[0:1]
	v_readlane_b32 s40, v253, 28
	v_readlane_b32 s41, v253, 29
	v_readlane_b32 s42, v253, 30
	v_readlane_b32 s43, v253, 31
	v_readlane_b32 s44, v253, 32
	v_readlane_b32 s45, v253, 33
	v_readlane_b32 s46, v253, 34
	v_readlane_b32 s47, v253, 35
	v_readlane_b32 s48, v253, 36
	v_readlane_b32 s49, v253, 37
	v_readlane_b32 s50, v253, 38
	v_readlane_b32 s51, v253, 39
	s_cbranch_vccnz .LBB0_410
	v_lshl_add_u64 v[38:39], v[166:167], 2, v[44:45]
	global_load_dwordx4 v[34:37], v[38:39], off offset:16
	s_nop 0
	global_load_dwordx4 v[38:41], v[38:39], off
	s_waitcnt vmcnt(0)
.LBB0_410:
	v_pk_fma_f32 v[26:27], v[26:27], v[78:79], v[34:35]
	v_lshl_add_u64 v[34:35], s[54:55], 0, v[46:47]
	v_pk_fma_f32 v[32:33], v[32:33], v[76:77], v[40:41]
	v_pk_fma_f32 v[30:31], v[30:31], v[74:75], v[38:39]
	v_pk_fma_f32 v[28:29], v[28:29], v[80:81], v[36:37]
	s_and_b64 vcc, exec, s[16:17]
	v_lshl_add_u64 v[34:35], v[166:167], 1, v[34:35]
	s_cbranch_vccnz .LBB0_412
	v_cvt_pk_bf16_f32 v36, v30, v31
	v_cvt_pk_bf16_f32 v37, v32, v33
	v_cvt_pk_bf16_f32 v38, v26, v27
	v_cvt_pk_bf16_f32 v39, v28, v29
	global_store_dwordx4 v[34:35], v[36:39], off

.LBB0_414:
	s_and_b64 vcc, exec, s[14:15]
	s_cbranch_vccnz .LBB0_423
	s_waitcnt vmcnt(8)
	v_lshlrev_b32_e32 v30, 16, v230
	v_and_b32_e32 v31, 0xffff0000, v230
	v_lshlrev_b32_e32 v32, 16, v231
	v_and_b32_e32 v33, 0xffff0000, v231
	v_lshlrev_b32_e32 v26, 16, v232
	v_and_b32_e32 v27, 0xffff0000, v232
	v_lshlrev_b32_e32 v28, 16, v233
	v_and_b32_e32 v29, 0xffff0000, v233
	s_cbranch_execnz .LBB0_417
.LBB0_416:
	v_lshl_add_u64 v[30:31], v[166:167], 2, v[44:45]
	global_load_dwordx4 v[26:29], v[30:31], off offset:528
	s_nop 0
	global_load_dwordx4 v[30:33], v[30:31], off offset:512
	s_waitcnt vmcnt(0)
.LBB0_417:
	v_pk_fma_f32 v[24:25], v[24:25], v[64:65], v[32:33]
	v_pk_fma_f32 v[22:23], v[22:23], v[62:63], v[30:31]
	v_pk_fma_f32 v[20:21], v[20:21], v[68:69], v[28:29]
	s_and_b64 vcc, exec, s[16:17]
	v_pk_fma_f32 v[18:19], v[18:19], v[66:67], v[26:27]
	s_cbranch_vccnz .LBB0_419
	v_cvt_pk_bf16_f32 v26, v22, v23
	v_cvt_pk_bf16_f32 v27, v24, v25
	v_cvt_pk_bf16_f32 v28, v18, v19
	v_cvt_pk_bf16_f32 v29, v20, v21
	global_store_dwordx4 v[34:35], v[26:29], off offset:256

.LBB0_421:
	v_add_u32_e32 v0, 0xc02, v186
	s_nop 0
	v_add_u32_e32 v18, 0xb0, v188
	v_cndmask_b32_e64 v28, v0, v18, s[10:11]
	v_ashrrev_i32_e32 v29, 31, v28
	v_lshlrev_b64 v[30:31], 11, v[28:29]
	v_lshl_add_u64 v[18:19], s[78:79], 0, v[30:31]
	v_cmp_gt_i32_e64 s[0:1], s7, v28
	s_and_b64 vcc, exec, s[14:15]
	v_lshl_add_u64 v[26:27], v[166:167], 1, v[18:19]
	s_cbranch_vccnz .LBB0_424
	s_waitcnt vmcnt(8)
	s_mov_b64 vcc, 0
	v_lshlrev_b32_e32 v22, 16, v234
	v_and_b32_e32 v23, 0xffff0000, v234
	v_lshlrev_b32_e32 v24, 16, v235
	v_and_b32_e32 v25, 0xffff0000, v235
	v_lshlrev_b32_e32 v18, 16, v236
	v_and_b32_e32 v19, 0xffff0000, v236
	v_lshlrev_b32_e32 v20, 16, v237
	v_and_b32_e32 v21, 0xffff0000, v237
	s_branch .LBB0_425

.LBB0_425:
	v_add_u32_e32 v0, 0xffffe000, v28
	v_readlane_b32 s36, v253, 24
	v_lshlrev_b64 v[34:35], 12, v[0:1]
	v_lshlrev_b64 v[32:33], 12, v[28:29]
	v_readlane_b32 s37, v253, 25
	v_readlane_b32 s38, v253, 26
	v_readlane_b32 s39, v253, 27
	v_lshl_add_u64 v[28:29], s[36:37], 0, v[32:33]
	s_andn2_b64 vcc, exec, vcc
	v_lshl_add_u64 v[34:35], s[38:39], 0, v[34:35]
	v_cndmask_b32_e64 v29, v35, v29, s[0:1]
	v_cndmask_b32_e64 v28, v34, v28, s[0:1]
	v_readlane_b32 s40, v253, 28
	v_readlane_b32 s41, v253, 29
	v_readlane_b32 s42, v253, 30
	v_readlane_b32 s43, v253, 31
	v_readlane_b32 s44, v253, 32
	v_readlane_b32 s45, v253, 33
	v_readlane_b32 s46, v253, 34
	v_readlane_b32 s47, v253, 35
	v_readlane_b32 s48, v253, 36
	v_readlane_b32 s49, v253, 37
	v_readlane_b32 s50, v253, 38
	v_readlane_b32 s51, v253, 39
	s_cbranch_vccnz .LBB0_427
	v_lshl_add_u64 v[22:23], v[166:167], 2, v[28:29]
	global_load_dwordx4 v[18:21], v[22:23], off offset:16
	s_nop 0
	global_load_dwordx4 v[22:25], v[22:23], off
	s_waitcnt vmcnt(0)
.LBB0_427:
	v_pk_fma_f32 v[10:11], v[10:11], v[78:79], v[18:19]
	v_lshl_add_u64 v[18:19], s[54:55], 0, v[30:31]
	v_pk_fma_f32 v[16:17], v[16:17], v[76:77], v[24:25]
	v_pk_fma_f32 v[14:15], v[14:15], v[74:75], v[22:23]
	v_pk_fma_f32 v[12:13], v[12:13], v[80:81], v[20:21]
	s_and_b64 vcc, exec, s[16:17]
	v_lshl_add_u64 v[18:19], v[166:167], 1, v[18:19]
	s_cbranch_vccnz .LBB0_429
	v_cvt_pk_bf16_f32 v20, v14, v15
	v_cvt_pk_bf16_f32 v21, v16, v17
	v_cvt_pk_bf16_f32 v22, v10, v11
	v_cvt_pk_bf16_f32 v23, v12, v13
	global_store_dwordx4 v[18:19], v[20:23], off

.LBB0_431:
	s_and_b64 vcc, exec, s[14:15]
	s_cbranch_vccnz .LBB0_441
	s_waitcnt vmcnt(8)
	v_lshlrev_b32_e32 v14, 16, v238
	v_and_b32_e32 v15, 0xffff0000, v238
	v_lshlrev_b32_e32 v16, 16, v239
	v_and_b32_e32 v17, 0xffff0000, v239
	v_lshlrev_b32_e32 v10, 16, v240
	v_and_b32_e32 v11, 0xffff0000, v240
	v_lshlrev_b32_e32 v12, 16, v241
	v_and_b32_e32 v13, 0xffff0000, v241
	s_cbranch_execnz .LBB0_434
.LBB0_433:
	v_lshl_add_u64 v[14:15], v[166:167], 2, v[28:29]
	global_load_dwordx4 v[10:13], v[14:15], off offset:528
	s_nop 0
	global_load_dwordx4 v[14:17], v[14:15], off offset:512
	s_waitcnt vmcnt(0)
.LBB0_434:
	v_pk_fma_f32 v[8:9], v[8:9], v[64:65], v[16:17]
	v_pk_fma_f32 v[6:7], v[6:7], v[62:63], v[14:15]
	v_pk_fma_f32 v[4:5], v[4:5], v[68:69], v[12:13]
	s_and_b64 vcc, exec, s[16:17]
	v_pk_fma_f32 v[2:3], v[2:3], v[66:67], v[10:11]
	s_cbranch_vccnz .LBB0_436
	v_cvt_pk_bf16_f32 v10, v6, v7
	v_cvt_pk_bf16_f32 v11, v8, v9
	v_cvt_pk_bf16_f32 v12, v2, v3
	v_cvt_pk_bf16_f32 v13, v4, v5
	global_store_dwordx4 v[18:19], v[10:13], off offset:256

.LBB0_478:
	v_lshlrev_b32_e32 v146, 6, v0
	v_mov_b32_e32 v147, s43
	v_add3_u32 v188, v146, s42, v147
	v_lshlrev_b32_e64 v146, 6, s42
	v_add3_u32 v189, v146, v0, s43
	v_cndmask_b32_e64 v170, v188, v189, s[10:11]
	v_ashrrev_i32_e32 v171, 31, v170
	v_lshlrev_b64 v[172:173], 11, v[170:171]
	v_cndmask_b32_e64 v0, 0, 1, s[52:53]
	v_lshl_add_u64 v[146:147], s[78:79], 0, v[172:173]
	v_cmp_gt_i32_e64 s[0:1], s7, v170
	v_cmp_ne_u32_e64 s[14:15], 1, v0
	s_andn2_b64 vcc, exec, s[52:53]
	v_lshl_add_u64 v[168:169], v[166:167], 1, v[146:147]
	s_cbranch_vccnz .LBB0_480
	v_add_u32_e32 v246, 0x0, v188
	v_add_u32_e32 v247, 0x0, v189
	v_cndmask_b32_e64 v246, v246, v247, s[10:11]
	v_ashrrev_i32_e32 v247, 31, v246
	v_lshlrev_b64 v[246:247], 11, v[246:247]
	v_lshl_add_u64 v[246:247], s[78:79], 0, v[246:247]
	v_lshl_add_u64 v[246:247], v[166:167], 1, v[246:247]
	global_load_dwordx4 v[192:195], v[246:247], off
	global_load_dwordx4 v[196:199], v[246:247], off offset:256
	v_add_u32_e32 v246, 0x400, v188
	v_add_u32_e32 v247, 0x10, v189
	v_cndmask_b32_e64 v246, v246, v247, s[10:11]
	v_ashrrev_i32_e32 v247, 31, v246
	v_lshlrev_b64 v[246:247], 11, v[246:247]
	v_lshl_add_u64 v[246:247], s[78:79], 0, v[246:247]
	v_lshl_add_u64 v[246:247], v[166:167], 1, v[246:247]
	global_load_dwordx4 v[218:221], v[246:247], off
	global_load_dwordx4 v[222:225], v[246:247], off offset:256
	v_add_u32_e32 v246, 0x800, v188
	v_add_u32_e32 v247, 0x20, v189
	v_cndmask_b32_e64 v246, v246, v247, s[10:11]
	v_ashrrev_i32_e32 v247, 31, v246
	v_lshlrev_b64 v[246:247], 11, v[246:247]
	v_lshl_add_u64 v[246:247], s[78:79], 0, v[246:247]
	v_lshl_add_u64 v[246:247], v[166:167], 1, v[246:247]
	global_load_dwordx4 v[226:229], v[246:247], off
	global_load_dwordx4 v[230:233], v[246:247], off offset:256
	v_add_u32_e32 v246, 0xc00, v188
	v_add_u32_e32 v247, 0x30, v189
	v_cndmask_b32_e64 v246, v246, v247, s[10:11]
	v_ashrrev_i32_e32 v247, 31, v246
	v_lshlrev_b64 v[246:247], 11, v[246:247]
	v_lshl_add_u64 v[246:247], s[78:79], 0, v[246:247]
	v_lshl_add_u64 v[246:247], v[166:167], 1, v[246:247]
	global_load_dwordx4 v[234:237], v[246:247], off
	global_load_dwordx4 v[238:241], v[246:247], off offset:256
	v_add_u32_e32 v246, 0x2, v188
	v_add_u32_e32 v247, 0x80, v189
	v_cndmask_b32_e64 v246, v246, v247, s[10:11]
	v_ashrrev_i32_e32 v247, 31, v246
	v_lshlrev_b64 v[246:247], 11, v[246:247]
	v_lshl_add_u64 v[246:247], s[78:79], 0, v[246:247]
	v_lshl_add_u64 v[246:247], v[166:167], 1, v[246:247]
	global_load_dwordx4 v[242:245], v[246:247], off
	global_load_dwordx4 v[242:245], v[246:247], off offset:256
	v_add_u32_e32 v246, 0x402, v188
	v_add_u32_e32 v247, 0x90, v189
	v_cndmask_b32_e64 v246, v246, v247, s[10:11]
	v_ashrrev_i32_e32 v247, 31, v246
	v_lshlrev_b64 v[246:247], 11, v[246:247]
	v_lshl_add_u64 v[246:247], s[78:79], 0, v[246:247]
	v_lshl_add_u64 v[246:247], v[166:167], 1, v[246:247]
	global_load_dwordx4 v[242:245], v[246:247], off
	global_load_dwordx4 v[242:245], v[246:247], off offset:256
	v_add_u32_e32 v246, 0x802, v188
	v_add_u32_e32 v247, 0xa0, v189
	v_cndmask_b32_e64 v246, v246, v247, s[10:11]
	v_ashrrev_i32_e32 v247, 31, v246
	v_lshlrev_b64 v[246:247], 11, v[246:247]
	v_lshl_add_u64 v[246:247], s[78:79], 0, v[246:247]
	v_lshl_add_u64 v[246:247], v[166:167], 1, v[246:247]
	global_load_dwordx4 v[242:245], v[246:247], off
	global_load_dwordx4 v[242:245], v[246:247], off offset:256
	v_add_u32_e32 v246, 0xc02, v188
	v_add_u32_e32 v247, 0xb0, v189
	v_cndmask_b32_e64 v246, v246, v247, s[10:11]
	v_ashrrev_i32_e32 v247, 31, v246
	v_lshlrev_b64 v[246:247], 11, v[246:247]
	v_lshl_add_u64 v[246:247], s[78:79], 0, v[246:247]
	v_lshl_add_u64 v[246:247], v[166:167], 1, v[246:247]
	global_load_dwordx4 v[242:245], v[246:247], off
	global_load_dwordx4 v[242:245], v[246:247], off offset:256
	s_waitcnt vmcnt(15)
	s_mov_b64 s[44:45], 0
	v_lshlrev_b32_e32 v150, 16, v192
	v_and_b32_e32 v151, 0xffff0000, v192
	v_lshlrev_b32_e32 v152, 16, v193
	v_and_b32_e32 v153, 0xffff0000, v193
	v_lshlrev_b32_e32 v146, 16, v194
	v_and_b32_e32 v147, 0xffff0000, v194
	v_lshlrev_b32_e32 v148, 16, v195
	v_and_b32_e32 v149, 0xffff0000, v195
	s_branch .LBB0_481

.LBB0_483:
	v_pk_fma_f32 v[138:139], v[138:139], v[78:79], v[146:147]
	v_cndmask_b32_e64 v0, 0, 1, s[96:97]
	v_lshl_add_u64 v[146:147], s[54:55], 0, v[172:173]
	v_pk_fma_f32 v[144:145], v[144:145], v[76:77], v[152:153]
	v_pk_fma_f32 v[142:143], v[142:143], v[74:75], v[150:151]
	v_pk_fma_f32 v[140:141], v[140:141], v[80:81], v[148:149]
	v_cmp_ne_u32_e64 s[18:19], 1, v0
	s_andn2_b64 vcc, exec, s[96:97]
	v_lshl_add_u64 v[146:147], v[166:167], 1, v[146:147]
	s_cbranch_vccnz .LBB0_485
	v_cvt_pk_bf16_f32 v148, v142, v143
	v_cvt_pk_bf16_f32 v149, v144, v145
	v_cvt_pk_bf16_f32 v150, v138, v139
	v_cvt_pk_bf16_f32 v151, v140, v141
	global_store_dwordx4 v[146:147], v[148:151], off

.LBB0_490:
	v_pk_fma_f32 v[136:137], v[136:137], v[64:65], v[144:145]
	v_pk_fma_f32 v[134:135], v[134:135], v[62:63], v[142:143]
	v_pk_fma_f32 v[132:133], v[132:133], v[68:69], v[140:141]
	s_and_b64 vcc, exec, s[18:19]
	v_pk_fma_f32 v[130:131], v[130:131], v[66:67], v[138:139]
	s_cbranch_vccnz .LBB0_492
	v_cvt_pk_bf16_f32 v138, v134, v135
	v_cvt_pk_bf16_f32 v139, v136, v137
	v_cvt_pk_bf16_f32 v140, v130, v131
	v_cvt_pk_bf16_f32 v141, v132, v133
	global_store_dwordx4 v[146:147], v[138:141], off offset:256

.LBB0_494:
	v_add_u32_e32 v0, 0x400, v188
	s_nop 0
	v_add_u32_e32 v130, 16, v189
	v_cndmask_b32_e64 v140, v0, v130, s[10:11]
	v_ashrrev_i32_e32 v141, 31, v140
	v_lshlrev_b64 v[142:143], 11, v[140:141]
	v_lshl_add_u64 v[130:131], s[78:79], 0, v[142:143]
	v_cmp_gt_i32_e64 s[0:1], s7, v140
	s_and_b64 vcc, exec, s[14:15]
	v_lshl_add_u64 v[138:139], v[166:167], 1, v[130:131]
	s_cbranch_vccnz .LBB0_497
	s_waitcnt vmcnt(15)
	s_mov_b64 vcc, 0
	v_lshlrev_b32_e32 v134, 16, v218
	v_and_b32_e32 v135, 0xffff0000, v218
	v_lshlrev_b32_e32 v136, 16, v219
	v_and_b32_e32 v137, 0xffff0000, v219
	v_lshlrev_b32_e32 v130, 16, v220
	v_and_b32_e32 v131, 0xffff0000, v220
	v_lshlrev_b32_e32 v132, 16, v221
	v_and_b32_e32 v133, 0xffff0000, v221
	s_branch .LBB0_498

.LBB0_500:
	v_pk_fma_f32 v[122:123], v[122:123], v[78:79], v[130:131]
	v_lshl_add_u64 v[130:131], s[54:55], 0, v[142:143]
	v_pk_fma_f32 v[128:129], v[128:129], v[76:77], v[136:137]
	v_pk_fma_f32 v[126:127], v[126:127], v[74:75], v[134:135]
	v_pk_fma_f32 v[124:125], v[124:125], v[80:81], v[132:133]
	s_and_b64 vcc, exec, s[18:19]
	v_lshl_add_u64 v[130:131], v[166:167], 1, v[130:131]
	s_cbranch_vccnz .LBB0_502
	v_cvt_pk_bf16_f32 v132, v126, v127
	v_cvt_pk_bf16_f32 v133, v128, v129
	v_cvt_pk_bf16_f32 v134, v122, v123
	v_cvt_pk_bf16_f32 v135, v124, v125
	global_store_dwordx4 v[130:131], v[132:135], off

.LBB0_507:
	v_pk_fma_f32 v[120:121], v[120:121], v[64:65], v[128:129]
	v_pk_fma_f32 v[118:119], v[118:119], v[62:63], v[126:127]
	v_pk_fma_f32 v[116:117], v[116:117], v[68:69], v[124:125]
	s_and_b64 vcc, exec, s[18:19]
	v_pk_fma_f32 v[114:115], v[114:115], v[66:67], v[122:123]
	s_cbranch_vccnz .LBB0_509
	v_cvt_pk_bf16_f32 v122, v118, v119
	v_cvt_pk_bf16_f32 v123, v120, v121
	v_cvt_pk_bf16_f32 v124, v114, v115
	v_cvt_pk_bf16_f32 v125, v116, v117
	global_store_dwordx4 v[130:131], v[122:125], off offset:256

.LBB0_511:
	v_add_u32_e32 v0, 0x800, v188
	s_nop 0
	v_add_u32_e32 v114, 32, v189
	v_cndmask_b32_e64 v124, v0, v114, s[10:11]
	v_ashrrev_i32_e32 v125, 31, v124
	v_lshlrev_b64 v[126:127], 11, v[124:125]
	v_lshl_add_u64 v[114:115], s[78:79], 0, v[126:127]
	v_cmp_gt_i32_e64 s[0:1], s7, v124
	s_and_b64 vcc, exec, s[14:15]
	v_lshl_add_u64 v[122:123], v[166:167], 1, v[114:115]
	s_cbranch_vccnz .LBB0_514
	s_waitcnt vmcnt(15)
	s_mov_b64 vcc, 0
	v_lshlrev_b32_e32 v118, 16, v226
	v_and_b32_e32 v119, 0xffff0000, v226
	v_lshlrev_b32_e32 v120, 16, v227
	v_and_b32_e32 v121, 0xffff0000, v227
	v_lshlrev_b32_e32 v114, 16, v228
	v_and_b32_e32 v115, 0xffff0000, v228
	v_lshlrev_b32_e32 v116, 16, v229
	v_and_b32_e32 v117, 0xffff0000, v229
	s_branch .LBB0_515

.LBB0_517:
	v_pk_fma_f32 v[106:107], v[106:107], v[78:79], v[114:115]
	v_lshl_add_u64 v[114:115], s[54:55], 0, v[126:127]
	v_pk_fma_f32 v[112:113], v[112:113], v[76:77], v[120:121]
	v_pk_fma_f32 v[110:111], v[110:111], v[74:75], v[118:119]
	v_pk_fma_f32 v[108:109], v[108:109], v[80:81], v[116:117]
	s_and_b64 vcc, exec, s[18:19]
	v_lshl_add_u64 v[114:115], v[166:167], 1, v[114:115]
	s_cbranch_vccnz .LBB0_519
	v_cvt_pk_bf16_f32 v116, v110, v111
	v_cvt_pk_bf16_f32 v117, v112, v113
	v_cvt_pk_bf16_f32 v118, v106, v107
	v_cvt_pk_bf16_f32 v119, v108, v109
	global_store_dwordx4 v[114:115], v[116:119], off

.LBB0_524:
	v_pk_fma_f32 v[104:105], v[104:105], v[64:65], v[112:113]
	v_pk_fma_f32 v[102:103], v[102:103], v[62:63], v[110:111]
	v_pk_fma_f32 v[100:101], v[100:101], v[68:69], v[108:109]
	s_and_b64 vcc, exec, s[18:19]
	v_pk_fma_f32 v[98:99], v[98:99], v[66:67], v[106:107]
	s_cbranch_vccnz .LBB0_526
	v_cvt_pk_bf16_f32 v106, v102, v103
	v_cvt_pk_bf16_f32 v107, v104, v105
	v_cvt_pk_bf16_f32 v108, v98, v99
	v_cvt_pk_bf16_f32 v109, v100, v101
	global_store_dwordx4 v[114:115], v[106:109], off offset:256

.LBB0_528:
	v_add_u32_e32 v0, 0xc00, v188
	s_nop 0
	v_add_u32_e32 v98, 48, v189
	v_cndmask_b32_e64 v108, v0, v98, s[10:11]
	v_ashrrev_i32_e32 v109, 31, v108
	v_lshlrev_b64 v[110:111], 11, v[108:109]
	v_lshl_add_u64 v[98:99], s[78:79], 0, v[110:111]
	v_cmp_gt_i32_e64 s[0:1], s7, v108
	s_and_b64 vcc, exec, s[14:15]
	v_lshl_add_u64 v[106:107], v[166:167], 1, v[98:99]
	s_cbranch_vccnz .LBB0_531
	s_waitcnt vmcnt(15)
	s_mov_b64 vcc, 0
	v_lshlrev_b32_e32 v102, 16, v234
	v_and_b32_e32 v103, 0xffff0000, v234
	v_lshlrev_b32_e32 v104, 16, v235
	v_and_b32_e32 v105, 0xffff0000, v235
	v_lshlrev_b32_e32 v98, 16, v236
	v_and_b32_e32 v99, 0xffff0000, v236
	v_lshlrev_b32_e32 v100, 16, v237
	v_and_b32_e32 v101, 0xffff0000, v237
	s_branch .LBB0_532

.LBB0_534:
	v_pk_fma_f32 v[90:91], v[90:91], v[78:79], v[98:99]
	v_lshl_add_u64 v[98:99], s[54:55], 0, v[110:111]
	v_pk_fma_f32 v[96:97], v[96:97], v[76:77], v[104:105]
	v_pk_fma_f32 v[94:95], v[94:95], v[74:75], v[102:103]
	v_pk_fma_f32 v[92:93], v[92:93], v[80:81], v[100:101]
	s_and_b64 vcc, exec, s[18:19]
	v_lshl_add_u64 v[98:99], v[166:167], 1, v[98:99]
	s_cbranch_vccnz .LBB0_536
	v_cvt_pk_bf16_f32 v100, v94, v95
	v_cvt_pk_bf16_f32 v101, v96, v97
	v_cvt_pk_bf16_f32 v102, v90, v91
	v_cvt_pk_bf16_f32 v103, v92, v93
	global_store_dwordx4 v[98:99], v[100:103], off

.LBB0_538:
	s_and_b64 vcc, exec, s[14:15]
	s_cbranch_vccnz .LBB0_547
	s_waitcnt vmcnt(15)
	v_lshlrev_b32_e32 v94, 16, v238
	v_and_b32_e32 v95, 0xffff0000, v238
	v_lshlrev_b32_e32 v96, 16, v239
	v_and_b32_e32 v97, 0xffff0000, v239
	v_lshlrev_b32_e32 v90, 16, v240
	v_and_b32_e32 v91, 0xffff0000, v240
	v_lshlrev_b32_e32 v92, 16, v241
	v_and_b32_e32 v93, 0xffff0000, v241
	v_add_u32_e32 v246, 0x2, v188
	v_add_u32_e32 v247, 0x80, v189
	v_cndmask_b32_e64 v246, v246, v247, s[10:11]
	v_ashrrev_i32_e32 v247, 31, v246
	v_lshlrev_b64 v[246:247], 11, v[246:247]
	v_lshl_add_u64 v[246:247], s[78:79], 0, v[246:247]
	v_lshl_add_u64 v[246:247], v[166:167], 1, v[246:247]
	global_load_dwordx4 v[192:195], v[246:247], off
	global_load_dwordx4 v[196:199], v[246:247], off offset:256
	v_add_u32_e32 v246, 0x402, v188
	v_add_u32_e32 v247, 0x90, v189
	v_cndmask_b32_e64 v246, v246, v247, s[10:11]
	v_ashrrev_i32_e32 v247, 31, v246
	v_lshlrev_b64 v[246:247], 11, v[246:247]
	v_lshl_add_u64 v[246:247], s[78:79], 0, v[246:247]
	v_lshl_add_u64 v[246:247], v[166:167], 1, v[246:247]
	global_load_dwordx4 v[218:221], v[246:247], off
	global_load_dwordx4 v[222:225], v[246:247], off offset:256
	v_add_u32_e32 v246, 0x802, v188
	v_add_u32_e32 v247, 0xa0, v189
	v_cndmask_b32_e64 v246, v246, v247, s[10:11]
	v_ashrrev_i32_e32 v247, 31, v246
	v_lshlrev_b64 v[246:247], 11, v[246:247]
	v_lshl_add_u64 v[246:247], s[78:79], 0, v[246:247]
	v_lshl_add_u64 v[246:247], v[166:167], 1, v[246:247]
	global_load_dwordx4 v[226:229], v[246:247], off
	global_load_dwordx4 v[230:233], v[246:247], off offset:256
	v_add_u32_e32 v246, 0xc02, v188
	v_add_u32_e32 v247, 0xb0, v189
	v_cndmask_b32_e64 v246, v246, v247, s[10:11]
	v_ashrrev_i32_e32 v247, 31, v246
	v_lshlrev_b64 v[246:247], 11, v[246:247]
	v_lshl_add_u64 v[246:247], s[78:79], 0, v[246:247]
	v_lshl_add_u64 v[246:247], v[166:167], 1, v[246:247]
	global_load_dwordx4 v[234:237], v[246:247], off
	global_load_dwordx4 v[238:241], v[246:247], off offset:256
	s_cbranch_execnz .LBB0_541

.LBB0_541:
	v_pk_fma_f32 v[88:89], v[88:89], v[64:65], v[96:97]
	v_pk_fma_f32 v[86:87], v[86:87], v[62:63], v[94:95]
	v_pk_fma_f32 v[84:85], v[84:85], v[68:69], v[92:93]
	s_and_b64 vcc, exec, s[18:19]
	v_pk_fma_f32 v[82:83], v[82:83], v[66:67], v[90:91]
	s_cbranch_vccnz .LBB0_543
	v_cvt_pk_bf16_f32 v90, v86, v87
	v_cvt_pk_bf16_f32 v91, v88, v89
	v_cvt_pk_bf16_f32 v92, v82, v83
	v_cvt_pk_bf16_f32 v93, v84, v85
	global_store_dwordx4 v[98:99], v[90:93], off offset:256

.LBB0_545:
	v_add_u32_e32 v0, 2, v188
	s_nop 0
	v_add_u32_e32 v82, 0x80, v189
	v_cndmask_b32_e64 v92, v0, v82, s[10:11]
	v_ashrrev_i32_e32 v93, 31, v92
	v_lshlrev_b64 v[94:95], 11, v[92:93]
	v_lshl_add_u64 v[82:83], s[78:79], 0, v[94:95]
	v_cmp_gt_i32_e64 s[0:1], s7, v92
	s_and_b64 vcc, exec, s[14:15]
	v_lshl_add_u64 v[90:91], v[166:167], 1, v[82:83]
	s_cbranch_vccnz .LBB0_548
	s_waitcnt vmcnt(8)
	s_mov_b64 vcc, 0
	v_lshlrev_b32_e32 v86, 16, v192
	v_and_b32_e32 v87, 0xffff0000, v192
	v_lshlrev_b32_e32 v88, 16, v193
	v_and_b32_e32 v89, 0xffff0000, v193
	v_lshlrev_b32_e32 v82, 16, v194
	v_and_b32_e32 v83, 0xffff0000, v194
	v_lshlrev_b32_e32 v84, 16, v195
	v_and_b32_e32 v85, 0xffff0000, v195
	s_branch .LBB0_549

.LBB0_551:
	v_pk_fma_f32 v[58:59], v[58:59], v[78:79], v[82:83]
	v_lshl_add_u64 v[82:83], s[54:55], 0, v[94:95]
	v_pk_fma_f32 v[72:73], v[72:73], v[76:77], v[88:89]
	v_pk_fma_f32 v[70:71], v[70:71], v[74:75], v[86:87]
	v_pk_fma_f32 v[60:61], v[60:61], v[80:81], v[84:85]
	s_and_b64 vcc, exec, s[18:19]
	v_lshl_add_u64 v[82:83], v[166:167], 1, v[82:83]
	s_cbranch_vccnz .LBB0_553
	v_cvt_pk_bf16_f32 v84, v70, v71
	v_cvt_pk_bf16_f32 v85, v72, v73
	v_cvt_pk_bf16_f32 v86, v58, v59
	v_cvt_pk_bf16_f32 v87, v60, v61
	global_store_dwordx4 v[82:83], v[84:87], off

.LBB0_558:
	v_pk_fma_f32 v[56:57], v[56:57], v[64:65], v[72:73]
	v_pk_fma_f32 v[54:55], v[54:55], v[62:63], v[70:71]
	v_pk_fma_f32 v[52:53], v[52:53], v[68:69], v[60:61]
	s_and_b64 vcc, exec, s[18:19]
	v_pk_fma_f32 v[50:51], v[50:51], v[66:67], v[58:59]
	s_cbranch_vccnz .LBB0_560
	v_cvt_pk_bf16_f32 v58, v54, v55
	v_cvt_pk_bf16_f32 v59, v56, v57
	v_cvt_pk_bf16_f32 v60, v50, v51
	v_cvt_pk_bf16_f32 v61, v52, v53
	global_store_dwordx4 v[82:83], v[58:61], off offset:256

.LBB0_562:
	v_add_u32_e32 v0, 0x402, v188
	s_nop 0
	v_add_u32_e32 v50, 0x90, v189
	v_cndmask_b32_e64 v60, v0, v50, s[10:11]
	v_ashrrev_i32_e32 v61, 31, v60
	v_lshlrev_b64 v[70:71], 11, v[60:61]
	v_lshl_add_u64 v[50:51], s[78:79], 0, v[70:71]
	v_cmp_gt_i32_e64 s[0:1], s7, v60
	s_and_b64 vcc, exec, s[14:15]
	v_lshl_add_u64 v[58:59], v[166:167], 1, v[50:51]
	s_cbranch_vccnz .LBB0_565
	s_waitcnt vmcnt(8)
	s_mov_b64 vcc, 0
	v_lshlrev_b32_e32 v54, 16, v218
	v_and_b32_e32 v55, 0xffff0000, v218
	v_lshlrev_b32_e32 v56, 16, v219
	v_and_b32_e32 v57, 0xffff0000, v219
	v_lshlrev_b32_e32 v50, 16, v220
	v_and_b32_e32 v51, 0xffff0000, v220
	v_lshlrev_b32_e32 v52, 16, v221
	v_and_b32_e32 v53, 0xffff0000, v221
	s_branch .LBB0_566

.LBB0_568:
	v_pk_fma_f32 v[42:43], v[42:43], v[78:79], v[50:51]
	v_lshl_add_u64 v[50:51], s[54:55], 0, v[70:71]
	v_pk_fma_f32 v[48:49], v[48:49], v[76:77], v[56:57]
	v_pk_fma_f32 v[46:47], v[46:47], v[74:75], v[54:55]
	v_pk_fma_f32 v[44:45], v[44:45], v[80:81], v[52:53]
	s_and_b64 vcc, exec, s[18:19]
	v_lshl_add_u64 v[50:51], v[166:167], 1, v[50:51]
	s_cbranch_vccnz .LBB0_570
	v_cvt_pk_bf16_f32 v52, v46, v47
	v_cvt_pk_bf16_f32 v53, v48, v49
	v_cvt_pk_bf16_f32 v54, v42, v43
	v_cvt_pk_bf16_f32 v55, v44, v45
	global_store_dwordx4 v[50:51], v[52:55], off

.LBB0_575:
	v_pk_fma_f32 v[40:41], v[40:41], v[64:65], v[48:49]
	v_pk_fma_f32 v[38:39], v[38:39], v[62:63], v[46:47]
	v_pk_fma_f32 v[36:37], v[36:37], v[68:69], v[44:45]
	s_and_b64 vcc, exec, s[18:19]
	v_pk_fma_f32 v[34:35], v[34:35], v[66:67], v[42:43]
	s_cbranch_vccnz .LBB0_577
	v_cvt_pk_bf16_f32 v42, v38, v39
	v_cvt_pk_bf16_f32 v43, v40, v41
	v_cvt_pk_bf16_f32 v44, v34, v35
	v_cvt_pk_bf16_f32 v45, v36, v37
	global_store_dwordx4 v[50:51], v[42:45], off offset:256

.LBB0_579:
	v_add_u32_e32 v0, 0x802, v188
	s_nop 0
	v_add_u32_e32 v34, 0xa0, v189
	v_cndmask_b32_e64 v44, v0, v34, s[10:11]
	v_ashrrev_i32_e32 v45, 31, v44
	v_lshlrev_b64 v[46:47], 11, v[44:45]
	v_lshl_add_u64 v[34:35], s[78:79], 0, v[46:47]
	v_cmp_gt_i32_e64 s[0:1], s7, v44
	s_and_b64 vcc, exec, s[14:15]
	v_lshl_add_u64 v[42:43], v[166:167], 1, v[34:35]
	s_cbranch_vccnz .LBB0_582
	s_waitcnt vmcnt(8)
	s_mov_b64 vcc, 0
	v_lshlrev_b32_e32 v38, 16, v226
	v_and_b32_e32 v39, 0xffff0000, v226
	v_lshlrev_b32_e32 v40, 16, v227
	v_and_b32_e32 v41, 0xffff0000, v227
	v_lshlrev_b32_e32 v34, 16, v228
	v_and_b32_e32 v35, 0xffff0000, v228
	v_lshlrev_b32_e32 v36, 16, v229
	v_and_b32_e32 v37, 0xffff0000, v229
	s_branch .LBB0_583

.LBB0_585:
	v_pk_fma_f32 v[26:27], v[26:27], v[78:79], v[34:35]
	v_lshl_add_u64 v[34:35], s[54:55], 0, v[46:47]
	v_pk_fma_f32 v[32:33], v[32:33], v[76:77], v[40:41]
	v_pk_fma_f32 v[30:31], v[30:31], v[74:75], v[38:39]
	v_pk_fma_f32 v[28:29], v[28:29], v[80:81], v[36:37]
	s_and_b64 vcc, exec, s[18:19]
	v_lshl_add_u64 v[34:35], v[166:167], 1, v[34:35]
	s_cbranch_vccnz .LBB0_587
	v_cvt_pk_bf16_f32 v36, v30, v31
	v_cvt_pk_bf16_f32 v37, v32, v33
	v_cvt_pk_bf16_f32 v38, v26, v27
	v_cvt_pk_bf16_f32 v39, v28, v29
	global_store_dwordx4 v[34:35], v[36:39], off

.LBB0_592:
	v_pk_fma_f32 v[24:25], v[24:25], v[64:65], v[32:33]
	v_pk_fma_f32 v[22:23], v[22:23], v[62:63], v[30:31]
	v_pk_fma_f32 v[20:21], v[20:21], v[68:69], v[28:29]
	s_and_b64 vcc, exec, s[18:19]
	v_pk_fma_f32 v[18:19], v[18:19], v[66:67], v[26:27]
	s_cbranch_vccnz .LBB0_594
	v_cvt_pk_bf16_f32 v26, v22, v23
	v_cvt_pk_bf16_f32 v27, v24, v25
	v_cvt_pk_bf16_f32 v28, v18, v19
	v_cvt_pk_bf16_f32 v29, v20, v21
	global_store_dwordx4 v[34:35], v[26:29], off offset:256

.LBB0_596:
	v_add_u32_e32 v0, 0xc02, v188
	s_nop 0
	v_add_u32_e32 v18, 0xb0, v189
	v_cndmask_b32_e64 v28, v0, v18, s[10:11]
	v_ashrrev_i32_e32 v29, 31, v28
	v_lshlrev_b64 v[30:31], 11, v[28:29]
	v_lshl_add_u64 v[18:19], s[78:79], 0, v[30:31]
	v_cmp_gt_i32_e64 s[0:1], s7, v28
	s_and_b64 vcc, exec, s[14:15]
	v_lshl_add_u64 v[26:27], v[166:167], 1, v[18:19]
	s_cbranch_vccnz .LBB0_599
	s_waitcnt vmcnt(8)
	s_mov_b64 vcc, 0
	v_lshlrev_b32_e32 v22, 16, v234
	v_and_b32_e32 v23, 0xffff0000, v234
	v_lshlrev_b32_e32 v24, 16, v235
	v_and_b32_e32 v25, 0xffff0000, v235
	v_lshlrev_b32_e32 v18, 16, v236
	v_and_b32_e32 v19, 0xffff0000, v236
	v_lshlrev_b32_e32 v20, 16, v237
	v_and_b32_e32 v21, 0xffff0000, v237
	s_branch .LBB0_600

.LBB0_602:
	v_pk_fma_f32 v[10:11], v[10:11], v[78:79], v[18:19]
	v_lshl_add_u64 v[18:19], s[54:55], 0, v[30:31]
	v_pk_fma_f32 v[16:17], v[16:17], v[76:77], v[24:25]
	v_pk_fma_f32 v[14:15], v[14:15], v[74:75], v[22:23]
	v_pk_fma_f32 v[12:13], v[12:13], v[80:81], v[20:21]
	s_and_b64 vcc, exec, s[18:19]
	v_lshl_add_u64 v[18:19], v[166:167], 1, v[18:19]
	s_cbranch_vccnz .LBB0_604
	v_cvt_pk_bf16_f32 v20, v14, v15
	v_cvt_pk_bf16_f32 v21, v16, v17
	v_cvt_pk_bf16_f32 v22, v10, v11
	v_cvt_pk_bf16_f32 v23, v12, v13
	global_store_dwordx4 v[18:19], v[20:23], off

.LBB0_609:
	v_pk_fma_f32 v[8:9], v[8:9], v[64:65], v[16:17]
	v_pk_fma_f32 v[6:7], v[6:7], v[62:63], v[14:15]
	v_pk_fma_f32 v[4:5], v[4:5], v[68:69], v[12:13]
	s_and_b64 vcc, exec, s[18:19]
	v_pk_fma_f32 v[2:3], v[2:3], v[66:67], v[10:11]
	s_cbranch_vccnz .LBB0_611
	v_cvt_pk_bf16_f32 v10, v6, v7
	v_cvt_pk_bf16_f32 v11, v8, v9
	v_cvt_pk_bf16_f32 v12, v2, v3
	v_cvt_pk_bf16_f32 v13, v4, v5
	global_store_dwordx4 v[18:19], v[10:13], off offset:256

.LBB0_649:
	v_lshlrev_b32_e32 v82, 6, v0
	v_mov_b32_e32 v83, s44
	v_add3_u32 v106, v82, s35, v83
	v_lshlrev_b32_e64 v82, 6, s35
	v_add3_u32 v107, v82, v0, s44
	v_add_u32_e32 v0, 2, v106
	v_add_u32_e32 v82, 0x80, v107
	v_cndmask_b32_e64 v100, v0, v82, s[10:11]
	v_ashrrev_i32_e32 v101, 31, v100
	v_lshlrev_b64 v[98:99], 11, v[100:101]
	v_cndmask_b32_e64 v0, 0, 1, s[76:77]
	v_lshl_add_u64 v[82:83], s[78:79], 0, v[98:99]
	v_cmp_gt_i32_e64 s[0:1], s73, v100
	v_cmp_ne_u32_e64 s[12:13], 1, v0
	s_andn2_b64 vcc, exec, s[76:77]
	v_lshl_add_u64 v[96:97], v[94:95], 1, v[82:83]
	s_cbranch_vccnz .LBB0_651
	v_add_u32_e32 v246, 0x2, v106
	v_add_u32_e32 v247, 0x80, v107
	v_cndmask_b32_e64 v246, v246, v247, s[10:11]
	v_ashrrev_i32_e32 v247, 31, v246
	v_lshlrev_b64 v[246:247], 11, v[246:247]
	v_lshl_add_u64 v[246:247], s[78:79], 0, v[246:247]
	v_lshl_add_u64 v[246:247], v[94:95], 1, v[246:247]
	global_load_dwordx4 v[110:113], v[246:247], off
	global_load_dwordx4 v[114:117], v[246:247], off offset:256
	v_add_u32_e32 v246, 0x402, v106
	v_add_u32_e32 v247, 0x90, v107
	v_cndmask_b32_e64 v246, v246, v247, s[10:11]
	v_ashrrev_i32_e32 v247, 31, v246
	v_lshlrev_b64 v[246:247], 11, v[246:247]
	v_lshl_add_u64 v[246:247], s[78:79], 0, v[246:247]
	v_lshl_add_u64 v[246:247], v[94:95], 1, v[246:247]
	global_load_dwordx4 v[118:121], v[246:247], off
	global_load_dwordx4 v[122:125], v[246:247], off offset:256
	v_add_u32_e32 v246, 0x802, v106
	v_add_u32_e32 v247, 0xa0, v107
	v_cndmask_b32_e64 v246, v246, v247, s[10:11]
	v_ashrrev_i32_e32 v247, 31, v246
	v_lshlrev_b64 v[246:247], 11, v[246:247]
	v_lshl_add_u64 v[246:247], s[78:79], 0, v[246:247]
	v_lshl_add_u64 v[246:247], v[94:95], 1, v[246:247]
	global_load_dwordx4 v[126:129], v[246:247], off
	global_load_dwordx4 v[130:133], v[246:247], off offset:256
	v_add_u32_e32 v246, 0xc02, v106
	v_add_u32_e32 v247, 0xb0, v107
	v_cndmask_b32_e64 v246, v246, v247, s[10:11]
	v_ashrrev_i32_e32 v247, 31, v246
	v_lshlrev_b64 v[246:247], 11, v[246:247]
	v_lshl_add_u64 v[246:247], s[78:79], 0, v[246:247]
	v_lshl_add_u64 v[246:247], v[94:95], 1, v[246:247]
	global_load_dwordx4 v[134:137], v[246:247], off
	global_load_dwordx4 v[238:241], v[246:247], off offset:256
	s_waitcnt vmcnt(7)
	s_mov_b64 s[46:47], 0
	v_lshlrev_b32_e32 v86, 16, v110
	v_and_b32_e32 v87, 0xffff0000, v110
	v_lshlrev_b32_e32 v88, 16, v111
	v_and_b32_e32 v89, 0xffff0000, v111
	v_lshlrev_b32_e32 v82, 16, v112
	v_and_b32_e32 v83, 0xffff0000, v112
	v_lshlrev_b32_e32 v84, 16, v113
	v_and_b32_e32 v85, 0xffff0000, v113
	s_branch .LBB0_652

.LBB0_652:
	v_add_u32_e32 v0, 0xffffe000, v100
	s_andn2_b64 vcc, exec, s[46:47]
	v_readlane_b32 s44, v253, 24
	v_lshlrev_b64 v[108:109], 12, v[0:1]
	v_lshlrev_b64 v[102:103], 12, v[100:101]
	v_readlane_b32 s45, v253, 25
	v_readlane_b32 s46, v253, 26
	v_readlane_b32 s47, v253, 27
	v_lshl_add_u64 v[100:101], s[44:45], 0, v[102:103]
	v_readlane_b32 s48, v253, 28
	v_lshl_add_u64 v[108:109], s[46:47], 0, v[108:109]
	v_cndmask_b32_e64 v101, v109, v101, s[0:1]
	v_cndmask_b32_e64 v100, v108, v100, s[0:1]
	v_readlane_b32 s49, v253, 29
	v_readlane_b32 s50, v253, 30
	v_readlane_b32 s51, v253, 31
	v_readlane_b32 s52, v253, 32
	v_readlane_b32 s53, v253, 33
	v_readlane_b32 s54, v253, 34
	v_readlane_b32 s55, v253, 35
	v_readlane_b32 s56, v253, 36
	v_readlane_b32 s57, v253, 37
	v_readlane_b32 s58, v253, 38
	v_readlane_b32 s59, v253, 39
	s_cbranch_vccnz .LBB0_654
	v_lshl_add_u64 v[86:87], v[94:95], 2, v[100:101]
	global_load_dwordx4 v[82:85], v[86:87], off offset:16
	s_nop 0
	global_load_dwordx4 v[86:89], v[86:87], off
	s_waitcnt vmcnt(0)
.LBB0_654:
	v_readlane_b32 s0, v253, 62
	v_readlane_b32 s1, v253, 63
	v_pk_fma_f32 v[74:75], v[74:75], v[54:55], v[82:83]
	v_cndmask_b32_e64 v0, 0, 1, s[92:93]
	v_lshl_add_u64 v[82:83], s[0:1], 0, v[98:99]
	v_pk_fma_f32 v[80:81], v[80:81], v[52:53], v[88:89]
	v_pk_fma_f32 v[78:79], v[78:79], v[50:51], v[86:87]
	v_pk_fma_f32 v[76:77], v[76:77], v[56:57], v[84:85]
	v_cmp_ne_u32_e64 s[20:21], 1, v0
	s_andn2_b64 vcc, exec, s[92:93]
	v_lshl_add_u64 v[82:83], v[94:95], 1, v[82:83]
	s_cbranch_vccnz .LBB0_656
	v_cvt_pk_bf16_f32 v84, v78, v79
	v_cvt_pk_bf16_f32 v85, v80, v81
	v_cvt_pk_bf16_f32 v86, v74, v75
	v_cvt_pk_bf16_f32 v87, v76, v77
	global_store_dwordx4 v[82:83], v[84:87], off

.LBB0_658:
	s_and_b64 vcc, exec, s[12:13]
	s_cbranch_vccnz .LBB0_667
	s_waitcnt vmcnt(7)
	v_lshlrev_b32_e32 v78, 16, v114
	v_and_b32_e32 v79, 0xffff0000, v114
	v_lshlrev_b32_e32 v80, 16, v115
	v_and_b32_e32 v81, 0xffff0000, v115
	v_lshlrev_b32_e32 v74, 16, v116
	v_and_b32_e32 v75, 0xffff0000, v116
	v_lshlrev_b32_e32 v76, 16, v117
	v_and_b32_e32 v77, 0xffff0000, v117
	s_cbranch_execnz .LBB0_661
.LBB0_660:
	v_lshl_add_u64 v[78:79], v[94:95], 2, v[100:101]
	global_load_dwordx4 v[74:77], v[78:79], off offset:528
	s_nop 0
	global_load_dwordx4 v[78:81], v[78:79], off offset:512
	s_waitcnt vmcnt(0)
.LBB0_661:
	v_pk_fma_f32 v[72:73], v[72:73], v[44:45], v[80:81]
	v_pk_fma_f32 v[70:71], v[70:71], v[42:43], v[78:79]
	v_pk_fma_f32 v[68:69], v[68:69], v[48:49], v[76:77]
	s_and_b64 vcc, exec, s[20:21]
	v_pk_fma_f32 v[66:67], v[66:67], v[46:47], v[74:75]
	s_cbranch_vccnz .LBB0_663
	v_cvt_pk_bf16_f32 v74, v70, v71
	v_cvt_pk_bf16_f32 v75, v72, v73
	v_cvt_pk_bf16_f32 v76, v66, v67
	v_cvt_pk_bf16_f32 v77, v68, v69
	global_store_dwordx4 v[82:83], v[74:77], off offset:256

.LBB0_665:
	v_add_u32_e32 v0, 0x402, v106
	s_nop 0
	v_add_u32_e32 v66, 0x90, v107
	v_cndmask_b32_e64 v78, v0, v66, s[10:11]
	v_ashrrev_i32_e32 v79, 31, v78
	v_lshlrev_b64 v[76:77], 11, v[78:79]
	v_lshl_add_u64 v[66:67], s[78:79], 0, v[76:77]
	v_cmp_gt_i32_e64 s[0:1], s73, v78
	s_and_b64 vcc, exec, s[12:13]
	v_lshl_add_u64 v[74:75], v[94:95], 1, v[66:67]
	s_cbranch_vccnz .LBB0_668
	s_waitcnt vmcnt(7)
	s_mov_b64 vcc, 0
	v_lshlrev_b32_e32 v70, 16, v118
	v_and_b32_e32 v71, 0xffff0000, v118
	v_lshlrev_b32_e32 v72, 16, v119
	v_and_b32_e32 v73, 0xffff0000, v119
	v_lshlrev_b32_e32 v66, 16, v120
	v_and_b32_e32 v67, 0xffff0000, v120
	v_lshlrev_b32_e32 v68, 16, v121
	v_and_b32_e32 v69, 0xffff0000, v121
	s_branch .LBB0_669

.LBB0_669:
	v_add_u32_e32 v0, 0xffffe000, v78
	v_readlane_b32 s44, v253, 24
	v_lshlrev_b64 v[82:83], 12, v[0:1]
	v_lshlrev_b64 v[80:81], 12, v[78:79]
	v_readlane_b32 s45, v253, 25
	v_readlane_b32 s46, v253, 26
	v_readlane_b32 s47, v253, 27
	v_lshl_add_u64 v[78:79], s[44:45], 0, v[80:81]
	s_andn2_b64 vcc, exec, vcc
	v_lshl_add_u64 v[82:83], s[46:47], 0, v[82:83]
	v_cndmask_b32_e64 v79, v83, v79, s[0:1]
	v_cndmask_b32_e64 v78, v82, v78, s[0:1]
	v_readlane_b32 s48, v253, 28
	v_readlane_b32 s49, v253, 29
	v_readlane_b32 s50, v253, 30
	v_readlane_b32 s51, v253, 31
	v_readlane_b32 s52, v253, 32
	v_readlane_b32 s53, v253, 33
	v_readlane_b32 s54, v253, 34
	v_readlane_b32 s55, v253, 35
	v_readlane_b32 s56, v253, 36
	v_readlane_b32 s57, v253, 37
	v_readlane_b32 s58, v253, 38
	v_readlane_b32 s59, v253, 39
	s_cbranch_vccnz .LBB0_671
	v_lshl_add_u64 v[70:71], v[94:95], 2, v[78:79]
	global_load_dwordx4 v[66:69], v[70:71], off offset:16
	s_nop 0
	global_load_dwordx4 v[70:73], v[70:71], off
	s_waitcnt vmcnt(0)
.LBB0_671:
	v_readlane_b32 s0, v253, 62
	v_readlane_b32 s1, v253, 63
	v_pk_fma_f32 v[58:59], v[58:59], v[54:55], v[66:67]
	v_pk_fma_f32 v[64:65], v[64:65], v[52:53], v[72:73]
	v_lshl_add_u64 v[66:67], s[0:1], 0, v[76:77]
	v_pk_fma_f32 v[62:63], v[62:63], v[50:51], v[70:71]
	v_pk_fma_f32 v[60:61], v[60:61], v[56:57], v[68:69]
	s_and_b64 vcc, exec, s[20:21]
	v_lshl_add_u64 v[66:67], v[94:95], 1, v[66:67]
	s_cbranch_vccnz .LBB0_673
	v_cvt_pk_bf16_f32 v68, v62, v63
	v_cvt_pk_bf16_f32 v69, v64, v65
	v_cvt_pk_bf16_f32 v70, v58, v59
	v_cvt_pk_bf16_f32 v71, v60, v61
	global_store_dwordx4 v[66:67], v[68:71], off

.LBB0_675:
	s_and_b64 vcc, exec, s[12:13]
	s_cbranch_vccnz .LBB0_684
	s_waitcnt vmcnt(7)
	v_lshlrev_b32_e32 v62, 16, v122
	v_and_b32_e32 v63, 0xffff0000, v122
	v_lshlrev_b32_e32 v64, 16, v123
	v_and_b32_e32 v65, 0xffff0000, v123
	v_lshlrev_b32_e32 v58, 16, v124
	v_and_b32_e32 v59, 0xffff0000, v124
	v_lshlrev_b32_e32 v60, 16, v125
	v_and_b32_e32 v61, 0xffff0000, v125
	s_cbranch_execnz .LBB0_678
.LBB0_677:
	v_lshl_add_u64 v[62:63], v[94:95], 2, v[78:79]
	global_load_dwordx4 v[58:61], v[62:63], off offset:528
	s_nop 0
	global_load_dwordx4 v[62:65], v[62:63], off offset:512
	s_waitcnt vmcnt(0)
.LBB0_678:
	v_pk_fma_f32 v[40:41], v[40:41], v[44:45], v[64:65]
	v_pk_fma_f32 v[38:39], v[38:39], v[42:43], v[62:63]
	v_pk_fma_f32 v[36:37], v[36:37], v[48:49], v[60:61]
	s_and_b64 vcc, exec, s[20:21]
	v_pk_fma_f32 v[34:35], v[34:35], v[46:47], v[58:59]
	s_cbranch_vccnz .LBB0_680
	v_cvt_pk_bf16_f32 v58, v38, v39
	v_cvt_pk_bf16_f32 v59, v40, v41
	v_cvt_pk_bf16_f32 v60, v34, v35
	v_cvt_pk_bf16_f32 v61, v36, v37
	global_store_dwordx4 v[66:67], v[58:61], off offset:256

.LBB0_682:
	v_add_u32_e32 v0, 0x802, v106
	s_nop 0
	v_add_u32_e32 v34, 0xa0, v107
	v_cndmask_b32_e64 v62, v0, v34, s[10:11]
	v_ashrrev_i32_e32 v63, 31, v62
	v_lshlrev_b64 v[60:61], 11, v[62:63]
	v_lshl_add_u64 v[34:35], s[78:79], 0, v[60:61]
	v_cmp_gt_i32_e64 s[0:1], s73, v62
	s_and_b64 vcc, exec, s[12:13]
	v_lshl_add_u64 v[58:59], v[94:95], 1, v[34:35]
	s_cbranch_vccnz .LBB0_685
	s_waitcnt vmcnt(7)
	s_mov_b64 vcc, 0
	v_lshlrev_b32_e32 v38, 16, v126
	v_and_b32_e32 v39, 0xffff0000, v126
	v_lshlrev_b32_e32 v40, 16, v127
	v_and_b32_e32 v41, 0xffff0000, v127
	v_lshlrev_b32_e32 v34, 16, v128
	v_and_b32_e32 v35, 0xffff0000, v128
	v_lshlrev_b32_e32 v36, 16, v129
	v_and_b32_e32 v37, 0xffff0000, v129
	s_branch .LBB0_686

.LBB0_686:
	v_add_u32_e32 v0, 0xffffe000, v62
	v_readlane_b32 s44, v253, 24
	v_lshlrev_b64 v[66:67], 12, v[0:1]
	v_lshlrev_b64 v[64:65], 12, v[62:63]
	v_readlane_b32 s45, v253, 25
	v_readlane_b32 s46, v253, 26
	v_readlane_b32 s47, v253, 27
	v_lshl_add_u64 v[62:63], s[44:45], 0, v[64:65]
	s_andn2_b64 vcc, exec, vcc
	v_lshl_add_u64 v[66:67], s[46:47], 0, v[66:67]
	v_cndmask_b32_e64 v63, v67, v63, s[0:1]
	v_cndmask_b32_e64 v62, v66, v62, s[0:1]
	v_readlane_b32 s48, v253, 28
	v_readlane_b32 s49, v253, 29
	v_readlane_b32 s50, v253, 30
	v_readlane_b32 s51, v253, 31
	v_readlane_b32 s52, v253, 32
	v_readlane_b32 s53, v253, 33
	v_readlane_b32 s54, v253, 34
	v_readlane_b32 s55, v253, 35
	v_readlane_b32 s56, v253, 36
	v_readlane_b32 s57, v253, 37
	v_readlane_b32 s58, v253, 38
	v_readlane_b32 s59, v253, 39
	s_cbranch_vccnz .LBB0_688
	v_lshl_add_u64 v[38:39], v[94:95], 2, v[62:63]
	global_load_dwordx4 v[34:37], v[38:39], off offset:16
	s_nop 0
	global_load_dwordx4 v[38:41], v[38:39], off
	s_waitcnt vmcnt(0)
.LBB0_688:
	v_readlane_b32 s0, v253, 62
	v_readlane_b32 s1, v253, 63
	v_pk_fma_f32 v[26:27], v[26:27], v[54:55], v[34:35]
	v_pk_fma_f32 v[32:33], v[32:33], v[52:53], v[40:41]
	v_lshl_add_u64 v[34:35], s[0:1], 0, v[60:61]
	v_pk_fma_f32 v[30:31], v[30:31], v[50:51], v[38:39]
	v_pk_fma_f32 v[28:29], v[28:29], v[56:57], v[36:37]
	s_and_b64 vcc, exec, s[20:21]
	v_lshl_add_u64 v[34:35], v[94:95], 1, v[34:35]
	s_cbranch_vccnz .LBB0_690
	v_cvt_pk_bf16_f32 v36, v30, v31
	v_cvt_pk_bf16_f32 v37, v32, v33
	v_cvt_pk_bf16_f32 v38, v26, v27
	v_cvt_pk_bf16_f32 v39, v28, v29
	global_store_dwordx4 v[34:35], v[36:39], off

.LBB0_692:
	s_and_b64 vcc, exec, s[12:13]
	s_cbranch_vccnz .LBB0_701
	s_waitcnt vmcnt(7)
	v_lshlrev_b32_e32 v30, 16, v130
	v_and_b32_e32 v31, 0xffff0000, v130
	v_lshlrev_b32_e32 v32, 16, v131
	v_and_b32_e32 v33, 0xffff0000, v131
	v_lshlrev_b32_e32 v26, 16, v132
	v_and_b32_e32 v27, 0xffff0000, v132
	v_lshlrev_b32_e32 v28, 16, v133
	v_and_b32_e32 v29, 0xffff0000, v133
	s_cbranch_execnz .LBB0_695
.LBB0_694:
	v_lshl_add_u64 v[30:31], v[94:95], 2, v[62:63]
	global_load_dwordx4 v[26:29], v[30:31], off offset:528
	s_nop 0
	global_load_dwordx4 v[30:33], v[30:31], off offset:512
	s_waitcnt vmcnt(0)
.LBB0_695:
	v_pk_fma_f32 v[24:25], v[24:25], v[44:45], v[32:33]
	v_pk_fma_f32 v[22:23], v[22:23], v[42:43], v[30:31]
	v_pk_fma_f32 v[20:21], v[20:21], v[48:49], v[28:29]
	s_and_b64 vcc, exec, s[20:21]
	v_pk_fma_f32 v[18:19], v[18:19], v[46:47], v[26:27]
	s_cbranch_vccnz .LBB0_697
	v_cvt_pk_bf16_f32 v26, v22, v23
	v_cvt_pk_bf16_f32 v27, v24, v25
	v_cvt_pk_bf16_f32 v28, v18, v19
	v_cvt_pk_bf16_f32 v29, v20, v21
	global_store_dwordx4 v[34:35], v[26:29], off offset:256

.LBB0_699:
	v_add_u32_e32 v0, 0xc02, v106
	s_nop 0
	v_add_u32_e32 v18, 0xb0, v107
	v_cndmask_b32_e64 v30, v0, v18, s[10:11]
	v_ashrrev_i32_e32 v31, 31, v30
	v_lshlrev_b64 v[28:29], 11, v[30:31]
	v_lshl_add_u64 v[18:19], s[78:79], 0, v[28:29]
	v_cmp_gt_i32_e64 s[0:1], s73, v30
	s_and_b64 vcc, exec, s[12:13]
	v_lshl_add_u64 v[26:27], v[94:95], 1, v[18:19]
	s_cbranch_vccnz .LBB0_702
	s_waitcnt vmcnt(7)
	s_mov_b64 vcc, 0
	v_lshlrev_b32_e32 v22, 16, v134
	v_and_b32_e32 v23, 0xffff0000, v134
	v_lshlrev_b32_e32 v24, 16, v135
	v_and_b32_e32 v25, 0xffff0000, v135
	v_lshlrev_b32_e32 v18, 16, v136
	v_and_b32_e32 v19, 0xffff0000, v136
	v_lshlrev_b32_e32 v20, 16, v137
	v_and_b32_e32 v21, 0xffff0000, v137
	s_branch .LBB0_703

.LBB0_703:
	v_add_u32_e32 v0, 0xffffe000, v30
	v_readlane_b32 s44, v253, 24
	v_lshlrev_b64 v[34:35], 12, v[0:1]
	v_lshlrev_b64 v[32:33], 12, v[30:31]
	v_readlane_b32 s45, v253, 25
	v_readlane_b32 s46, v253, 26
	v_readlane_b32 s47, v253, 27
	v_lshl_add_u64 v[30:31], s[44:45], 0, v[32:33]
	s_andn2_b64 vcc, exec, vcc
	v_lshl_add_u64 v[34:35], s[46:47], 0, v[34:35]
	v_cndmask_b32_e64 v31, v35, v31, s[0:1]
	v_cndmask_b32_e64 v30, v34, v30, s[0:1]
	v_readlane_b32 s48, v253, 28
	v_readlane_b32 s49, v253, 29
	v_readlane_b32 s50, v253, 30
	v_readlane_b32 s51, v253, 31
	v_readlane_b32 s52, v253, 32
	v_readlane_b32 s53, v253, 33
	v_readlane_b32 s54, v253, 34
	v_readlane_b32 s55, v253, 35
	v_readlane_b32 s56, v253, 36
	v_readlane_b32 s57, v253, 37
	v_readlane_b32 s58, v253, 38
	v_readlane_b32 s59, v253, 39
	s_cbranch_vccnz .LBB0_705
	v_lshl_add_u64 v[22:23], v[94:95], 2, v[30:31]
	global_load_dwordx4 v[18:21], v[22:23], off offset:16
	s_nop 0
	global_load_dwordx4 v[22:25], v[22:23], off
	s_waitcnt vmcnt(0)
.LBB0_705:
	v_readlane_b32 s54, v253, 62
	v_readlane_b32 s55, v253, 63
	v_pk_fma_f32 v[10:11], v[10:11], v[54:55], v[18:19]
	v_pk_fma_f32 v[16:17], v[16:17], v[52:53], v[24:25]
	v_lshl_add_u64 v[18:19], s[54:55], 0, v[28:29]
	v_pk_fma_f32 v[14:15], v[14:15], v[50:51], v[22:23]
	v_pk_fma_f32 v[12:13], v[12:13], v[56:57], v[20:21]
	s_and_b64 vcc, exec, s[20:21]
	v_lshl_add_u64 v[18:19], v[94:95], 1, v[18:19]
	s_cbranch_vccnz .LBB0_707
	v_cvt_pk_bf16_f32 v20, v14, v15
	v_cvt_pk_bf16_f32 v21, v16, v17
	v_cvt_pk_bf16_f32 v22, v10, v11
	v_cvt_pk_bf16_f32 v23, v12, v13
	global_store_dwordx4 v[18:19], v[20:23], off

.LBB0_709:
	s_and_b64 vcc, exec, s[12:13]
	s_cbranch_vccnz .LBB0_719
	s_waitcnt vmcnt(7)
	v_lshlrev_b32_e32 v14, 16, v238
	v_and_b32_e32 v15, 0xffff0000, v238
	v_lshlrev_b32_e32 v16, 16, v239
	v_and_b32_e32 v17, 0xffff0000, v239
	v_lshlrev_b32_e32 v10, 16, v240
	v_and_b32_e32 v11, 0xffff0000, v240
	v_lshlrev_b32_e32 v12, 16, v241
	v_and_b32_e32 v13, 0xffff0000, v241
	s_cbranch_execnz .LBB0_712
.LBB0_711:
	v_lshl_add_u64 v[14:15], v[94:95], 2, v[30:31]
	global_load_dwordx4 v[10:13], v[14:15], off offset:528
	s_nop 0
	global_load_dwordx4 v[14:17], v[14:15], off offset:512
	s_waitcnt vmcnt(0)
.LBB0_712:
	v_pk_fma_f32 v[8:9], v[8:9], v[44:45], v[16:17]
	v_pk_fma_f32 v[6:7], v[6:7], v[42:43], v[14:15]
	v_pk_fma_f32 v[4:5], v[4:5], v[48:49], v[12:13]
	s_and_b64 vcc, exec, s[20:21]
	v_pk_fma_f32 v[2:3], v[2:3], v[46:47], v[10:11]
	s_cbranch_vccnz .LBB0_714
	v_cvt_pk_bf16_f32 v10, v6, v7
	v_cvt_pk_bf16_f32 v11, v8, v9
	v_cvt_pk_bf16_f32 v12, v2, v3
	v_cvt_pk_bf16_f32 v13, v4, v5
	global_store_dwordx4 v[18:19], v[10:13], off offset:256

.LBB0_753:
	v_lshlrev_b32_e32 v82, 6, v0
	v_mov_b32_e32 v83, s42
	v_add3_u32 v106, v82, s35, v83
	v_lshlrev_b32_e64 v82, 6, s35
	v_add3_u32 v107, v82, v0, s42
	v_cndmask_b32_e64 v98, v106, v107, s[10:11]
	v_ashrrev_i32_e32 v99, 31, v98
	v_lshlrev_b64 v[100:101], 11, v[98:99]
	v_cndmask_b32_e64 v0, 0, 1, s[68:69]
	v_lshl_add_u64 v[82:83], s[78:79], 0, v[100:101]
	v_cmp_gt_i32_e64 s[0:1], s73, v98
	v_cmp_ne_u32_e64 s[14:15], 1, v0
	s_andn2_b64 vcc, exec, s[68:69]
	v_lshl_add_u64 v[96:97], v[94:95], 1, v[82:83]
	s_cbranch_vccnz .LBB0_755
	v_add_u32_e32 v246, 0x0, v106
	v_add_u32_e32 v247, 0x0, v107
	v_cndmask_b32_e64 v246, v246, v247, s[10:11]
	v_ashrrev_i32_e32 v247, 31, v246
	v_lshlrev_b64 v[246:247], 11, v[246:247]
	v_lshl_add_u64 v[246:247], s[78:79], 0, v[246:247]
	v_lshl_add_u64 v[246:247], v[94:95], 1, v[246:247]
	global_load_dwordx4 v[110:113], v[246:247], off
	global_load_dwordx4 v[114:117], v[246:247], off offset:256
	v_add_u32_e32 v246, 0x400, v106
	v_add_u32_e32 v247, 0x10, v107
	v_cndmask_b32_e64 v246, v246, v247, s[10:11]
	v_ashrrev_i32_e32 v247, 31, v246
	v_lshlrev_b64 v[246:247], 11, v[246:247]
	v_lshl_add_u64 v[246:247], s[78:79], 0, v[246:247]
	v_lshl_add_u64 v[246:247], v[94:95], 1, v[246:247]
	global_load_dwordx4 v[118:121], v[246:247], off
	global_load_dwordx4 v[122:125], v[246:247], off offset:256
	v_add_u32_e32 v246, 0x800, v106
	v_add_u32_e32 v247, 0x20, v107
	v_cndmask_b32_e64 v246, v246, v247, s[10:11]
	v_ashrrev_i32_e32 v247, 31, v246
	v_lshlrev_b64 v[246:247], 11, v[246:247]
	v_lshl_add_u64 v[246:247], s[78:79], 0, v[246:247]
	v_lshl_add_u64 v[246:247], v[94:95], 1, v[246:247]
	global_load_dwordx4 v[126:129], v[246:247], off
	global_load_dwordx4 v[130:133], v[246:247], off offset:256
	v_add_u32_e32 v246, 0xc00, v106
	v_add_u32_e32 v247, 0x30, v107
	v_cndmask_b32_e64 v246, v246, v247, s[10:11]
	v_ashrrev_i32_e32 v247, 31, v246
	v_lshlrev_b64 v[246:247], 11, v[246:247]
	v_lshl_add_u64 v[246:247], s[78:79], 0, v[246:247]
	v_lshl_add_u64 v[246:247], v[94:95], 1, v[246:247]
	global_load_dwordx4 v[134:137], v[246:247], off
	global_load_dwordx4 v[238:241], v[246:247], off offset:256
	s_waitcnt vmcnt(7)
	s_mov_b64 s[44:45], 0
	v_lshlrev_b32_e32 v86, 16, v110
	v_and_b32_e32 v87, 0xffff0000, v110
	v_lshlrev_b32_e32 v88, 16, v111
	v_and_b32_e32 v89, 0xffff0000, v111
	v_lshlrev_b32_e32 v82, 16, v112
	v_and_b32_e32 v83, 0xffff0000, v112
	v_lshlrev_b32_e32 v84, 16, v113
	v_and_b32_e32 v85, 0xffff0000, v113
	s_branch .LBB0_756

.LBB0_756:
	v_add_u32_e32 v0, 0xffffe000, v98
	s_andn2_b64 vcc, exec, s[44:45]
	v_readlane_b32 s36, v253, 24
	v_lshlrev_b64 v[108:109], 12, v[0:1]
	v_lshlrev_b64 v[102:103], 12, v[98:99]
	v_readlane_b32 s37, v253, 25
	v_readlane_b32 s38, v253, 26
	v_readlane_b32 s39, v253, 27
	v_lshl_add_u64 v[98:99], s[36:37], 0, v[102:103]
	v_readlane_b32 s40, v253, 28
	v_lshl_add_u64 v[108:109], s[38:39], 0, v[108:109]
	v_cndmask_b32_e64 v99, v109, v99, s[0:1]
	v_cndmask_b32_e64 v98, v108, v98, s[0:1]
	v_readlane_b32 s41, v253, 29
	v_readlane_b32 s42, v253, 30
	v_readlane_b32 s43, v253, 31
	v_readlane_b32 s44, v253, 32
	v_readlane_b32 s45, v253, 33
	v_readlane_b32 s46, v253, 34
	v_readlane_b32 s47, v253, 35
	v_readlane_b32 s48, v253, 36
	v_readlane_b32 s49, v253, 37
	v_readlane_b32 s50, v253, 38
	v_readlane_b32 s51, v253, 39
	s_cbranch_vccnz .LBB0_758
	v_lshl_add_u64 v[86:87], v[94:95], 2, v[98:99]
	global_load_dwordx4 v[82:85], v[86:87], off offset:16
	s_nop 0
	global_load_dwordx4 v[86:89], v[86:87], off
	s_waitcnt vmcnt(0)
.LBB0_758:
	v_pk_fma_f32 v[74:75], v[74:75], v[54:55], v[82:83]
	v_cndmask_b32_e64 v0, 0, 1, s[76:77]
	v_lshl_add_u64 v[82:83], s[54:55], 0, v[100:101]
	v_pk_fma_f32 v[80:81], v[80:81], v[52:53], v[88:89]
	v_pk_fma_f32 v[78:79], v[78:79], v[50:51], v[86:87]
	v_pk_fma_f32 v[76:77], v[76:77], v[56:57], v[84:85]
	v_cmp_ne_u32_e64 s[18:19], 1, v0
	s_andn2_b64 vcc, exec, s[76:77]
	v_lshl_add_u64 v[82:83], v[94:95], 1, v[82:83]
	s_cbranch_vccnz .LBB0_760
	v_cvt_pk_bf16_f32 v84, v78, v79
	v_cvt_pk_bf16_f32 v85, v80, v81
	v_cvt_pk_bf16_f32 v86, v74, v75
	v_cvt_pk_bf16_f32 v87, v76, v77
	global_store_dwordx4 v[82:83], v[84:87], off

.LBB0_762:
	s_and_b64 vcc, exec, s[14:15]
	s_cbranch_vccnz .LBB0_771
	s_waitcnt vmcnt(7)
	v_lshlrev_b32_e32 v78, 16, v114
	v_and_b32_e32 v79, 0xffff0000, v114
	v_lshlrev_b32_e32 v80, 16, v115
	v_and_b32_e32 v81, 0xffff0000, v115
	v_lshlrev_b32_e32 v74, 16, v116
	v_and_b32_e32 v75, 0xffff0000, v116
	v_lshlrev_b32_e32 v76, 16, v117
	v_and_b32_e32 v77, 0xffff0000, v117
	s_cbranch_execnz .LBB0_765
.LBB0_764:
	v_lshl_add_u64 v[78:79], v[94:95], 2, v[98:99]
	global_load_dwordx4 v[74:77], v[78:79], off offset:528
	s_nop 0
	global_load_dwordx4 v[78:81], v[78:79], off offset:512
	s_waitcnt vmcnt(0)
.LBB0_765:
	v_pk_fma_f32 v[72:73], v[72:73], v[44:45], v[80:81]
	v_pk_fma_f32 v[70:71], v[70:71], v[42:43], v[78:79]
	v_pk_fma_f32 v[68:69], v[68:69], v[48:49], v[76:77]
	s_and_b64 vcc, exec, s[18:19]
	v_pk_fma_f32 v[66:67], v[66:67], v[46:47], v[74:75]
	s_cbranch_vccnz .LBB0_767
	v_cvt_pk_bf16_f32 v74, v70, v71
	v_cvt_pk_bf16_f32 v75, v72, v73
	v_cvt_pk_bf16_f32 v76, v66, v67
	v_cvt_pk_bf16_f32 v77, v68, v69
	global_store_dwordx4 v[82:83], v[74:77], off offset:256

.LBB0_769:
	v_add_u32_e32 v0, 0x400, v106
	s_nop 0
	v_add_u32_e32 v66, 16, v107
	v_cndmask_b32_e64 v76, v0, v66, s[10:11]
	v_ashrrev_i32_e32 v77, 31, v76
	v_lshlrev_b64 v[78:79], 11, v[76:77]
	v_lshl_add_u64 v[66:67], s[78:79], 0, v[78:79]
	v_cmp_gt_i32_e64 s[0:1], s73, v76
	s_and_b64 vcc, exec, s[14:15]
	v_lshl_add_u64 v[74:75], v[94:95], 1, v[66:67]
	s_cbranch_vccnz .LBB0_772
	s_waitcnt vmcnt(7)
	s_mov_b64 vcc, 0
	v_lshlrev_b32_e32 v70, 16, v118
	v_and_b32_e32 v71, 0xffff0000, v118
	v_lshlrev_b32_e32 v72, 16, v119
	v_and_b32_e32 v73, 0xffff0000, v119
	v_lshlrev_b32_e32 v66, 16, v120
	v_and_b32_e32 v67, 0xffff0000, v120
	v_lshlrev_b32_e32 v68, 16, v121
	v_and_b32_e32 v69, 0xffff0000, v121
	s_branch .LBB0_773

.LBB0_773:
	v_add_u32_e32 v0, 0xffffe000, v76
	v_readlane_b32 s36, v253, 24
	v_lshlrev_b64 v[82:83], 12, v[0:1]
	v_lshlrev_b64 v[80:81], 12, v[76:77]
	v_readlane_b32 s37, v253, 25
	v_readlane_b32 s38, v253, 26
	v_readlane_b32 s39, v253, 27
	v_lshl_add_u64 v[76:77], s[36:37], 0, v[80:81]
	s_andn2_b64 vcc, exec, vcc
	v_lshl_add_u64 v[82:83], s[38:39], 0, v[82:83]
	v_cndmask_b32_e64 v77, v83, v77, s[0:1]
	v_cndmask_b32_e64 v76, v82, v76, s[0:1]
	v_readlane_b32 s40, v253, 28
	v_readlane_b32 s41, v253, 29
	v_readlane_b32 s42, v253, 30
	v_readlane_b32 s43, v253, 31
	v_readlane_b32 s44, v253, 32
	v_readlane_b32 s45, v253, 33
	v_readlane_b32 s46, v253, 34
	v_readlane_b32 s47, v253, 35
	v_readlane_b32 s48, v253, 36
	v_readlane_b32 s49, v253, 37
	v_readlane_b32 s50, v253, 38
	v_readlane_b32 s51, v253, 39
	s_cbranch_vccnz .LBB0_775
	v_lshl_add_u64 v[70:71], v[94:95], 2, v[76:77]
	global_load_dwordx4 v[66:69], v[70:71], off offset:16
	s_nop 0
	global_load_dwordx4 v[70:73], v[70:71], off
	s_waitcnt vmcnt(0)
.LBB0_775:
	v_pk_fma_f32 v[58:59], v[58:59], v[54:55], v[66:67]
	v_lshl_add_u64 v[66:67], s[54:55], 0, v[78:79]
	v_pk_fma_f32 v[64:65], v[64:65], v[52:53], v[72:73]
	v_pk_fma_f32 v[62:63], v[62:63], v[50:51], v[70:71]
	v_pk_fma_f32 v[60:61], v[60:61], v[56:57], v[68:69]
	s_and_b64 vcc, exec, s[18:19]
	v_lshl_add_u64 v[66:67], v[94:95], 1, v[66:67]
	s_cbranch_vccnz .LBB0_777
	v_cvt_pk_bf16_f32 v68, v62, v63
	v_cvt_pk_bf16_f32 v69, v64, v65
	v_cvt_pk_bf16_f32 v70, v58, v59
	v_cvt_pk_bf16_f32 v71, v60, v61
	global_store_dwordx4 v[66:67], v[68:71], off

.LBB0_779:
	s_and_b64 vcc, exec, s[14:15]
	s_cbranch_vccnz .LBB0_788
	s_waitcnt vmcnt(7)
	v_lshlrev_b32_e32 v62, 16, v122
	v_and_b32_e32 v63, 0xffff0000, v122
	v_lshlrev_b32_e32 v64, 16, v123
	v_and_b32_e32 v65, 0xffff0000, v123
	v_lshlrev_b32_e32 v58, 16, v124
	v_and_b32_e32 v59, 0xffff0000, v124
	v_lshlrev_b32_e32 v60, 16, v125
	v_and_b32_e32 v61, 0xffff0000, v125
	s_cbranch_execnz .LBB0_782
.LBB0_781:
	v_lshl_add_u64 v[62:63], v[94:95], 2, v[76:77]
	global_load_dwordx4 v[58:61], v[62:63], off offset:528
	s_nop 0
	global_load_dwordx4 v[62:65], v[62:63], off offset:512
	s_waitcnt vmcnt(0)
.LBB0_782:
	v_pk_fma_f32 v[40:41], v[40:41], v[44:45], v[64:65]
	v_pk_fma_f32 v[38:39], v[38:39], v[42:43], v[62:63]
	v_pk_fma_f32 v[36:37], v[36:37], v[48:49], v[60:61]
	s_and_b64 vcc, exec, s[18:19]
	v_pk_fma_f32 v[34:35], v[34:35], v[46:47], v[58:59]
	s_cbranch_vccnz .LBB0_784
	v_cvt_pk_bf16_f32 v58, v38, v39
	v_cvt_pk_bf16_f32 v59, v40, v41
	v_cvt_pk_bf16_f32 v60, v34, v35
	v_cvt_pk_bf16_f32 v61, v36, v37
	global_store_dwordx4 v[66:67], v[58:61], off offset:256

.LBB0_786:
	v_add_u32_e32 v0, 0x800, v106
	s_nop 0
	v_add_u32_e32 v34, 32, v107
	v_cndmask_b32_e64 v60, v0, v34, s[10:11]
	v_ashrrev_i32_e32 v61, 31, v60
	v_lshlrev_b64 v[62:63], 11, v[60:61]
	v_lshl_add_u64 v[34:35], s[78:79], 0, v[62:63]
	v_cmp_gt_i32_e64 s[0:1], s73, v60
	s_and_b64 vcc, exec, s[14:15]
	v_lshl_add_u64 v[58:59], v[94:95], 1, v[34:35]
	s_cbranch_vccnz .LBB0_789
	s_waitcnt vmcnt(7)
	s_mov_b64 vcc, 0
	v_lshlrev_b32_e32 v38, 16, v126
	v_and_b32_e32 v39, 0xffff0000, v126
	v_lshlrev_b32_e32 v40, 16, v127
	v_and_b32_e32 v41, 0xffff0000, v127
	v_lshlrev_b32_e32 v34, 16, v128
	v_and_b32_e32 v35, 0xffff0000, v128
	v_lshlrev_b32_e32 v36, 16, v129
	v_and_b32_e32 v37, 0xffff0000, v129
	s_branch .LBB0_790

.LBB0_790:
	v_add_u32_e32 v0, 0xffffe000, v60
	v_readlane_b32 s36, v253, 24
	v_lshlrev_b64 v[66:67], 12, v[0:1]
	v_lshlrev_b64 v[64:65], 12, v[60:61]
	v_readlane_b32 s37, v253, 25
	v_readlane_b32 s38, v253, 26
	v_readlane_b32 s39, v253, 27
	v_lshl_add_u64 v[60:61], s[36:37], 0, v[64:65]
	s_andn2_b64 vcc, exec, vcc
	v_lshl_add_u64 v[66:67], s[38:39], 0, v[66:67]
	v_cndmask_b32_e64 v61, v67, v61, s[0:1]
	v_cndmask_b32_e64 v60, v66, v60, s[0:1]
	v_readlane_b32 s40, v253, 28
	v_readlane_b32 s41, v253, 29
	v_readlane_b32 s42, v253, 30
	v_readlane_b32 s43, v253, 31
	v_readlane_b32 s44, v253, 32
	v_readlane_b32 s45, v253, 33
	v_readlane_b32 s46, v253, 34
	v_readlane_b32 s47, v253, 35
	v_readlane_b32 s48, v253, 36
	v_readlane_b32 s49, v253, 37
	v_readlane_b32 s50, v253, 38
	v_readlane_b32 s51, v253, 39
	s_cbranch_vccnz .LBB0_792
	v_lshl_add_u64 v[38:39], v[94:95], 2, v[60:61]
	global_load_dwordx4 v[34:37], v[38:39], off offset:16
	s_nop 0
	global_load_dwordx4 v[38:41], v[38:39], off
	s_waitcnt vmcnt(0)
.LBB0_792:
	v_pk_fma_f32 v[26:27], v[26:27], v[54:55], v[34:35]
	v_lshl_add_u64 v[34:35], s[54:55], 0, v[62:63]
	v_pk_fma_f32 v[32:33], v[32:33], v[52:53], v[40:41]
	v_pk_fma_f32 v[30:31], v[30:31], v[50:51], v[38:39]
	v_pk_fma_f32 v[28:29], v[28:29], v[56:57], v[36:37]
	s_and_b64 vcc, exec, s[18:19]
	v_lshl_add_u64 v[34:35], v[94:95], 1, v[34:35]
	s_cbranch_vccnz .LBB0_794
	v_cvt_pk_bf16_f32 v36, v30, v31
	v_cvt_pk_bf16_f32 v37, v32, v33
	v_cvt_pk_bf16_f32 v38, v26, v27
	v_cvt_pk_bf16_f32 v39, v28, v29
	global_store_dwordx4 v[34:35], v[36:39], off

.LBB0_796:
	s_and_b64 vcc, exec, s[14:15]
	s_cbranch_vccnz .LBB0_805
	s_waitcnt vmcnt(7)
	v_lshlrev_b32_e32 v30, 16, v130
	v_and_b32_e32 v31, 0xffff0000, v130
	v_lshlrev_b32_e32 v32, 16, v131
	v_and_b32_e32 v33, 0xffff0000, v131
	v_lshlrev_b32_e32 v26, 16, v132
	v_and_b32_e32 v27, 0xffff0000, v132
	v_lshlrev_b32_e32 v28, 16, v133
	v_and_b32_e32 v29, 0xffff0000, v133
	s_cbranch_execnz .LBB0_799
.LBB0_798:
	v_lshl_add_u64 v[30:31], v[94:95], 2, v[60:61]
	global_load_dwordx4 v[26:29], v[30:31], off offset:528
	s_nop 0
	global_load_dwordx4 v[30:33], v[30:31], off offset:512
	s_waitcnt vmcnt(0)
.LBB0_799:
	v_pk_fma_f32 v[24:25], v[24:25], v[44:45], v[32:33]
	v_pk_fma_f32 v[22:23], v[22:23], v[42:43], v[30:31]
	v_pk_fma_f32 v[20:21], v[20:21], v[48:49], v[28:29]
	s_and_b64 vcc, exec, s[18:19]
	v_pk_fma_f32 v[18:19], v[18:19], v[46:47], v[26:27]
	s_cbranch_vccnz .LBB0_801
	v_cvt_pk_bf16_f32 v26, v22, v23
	v_cvt_pk_bf16_f32 v27, v24, v25
	v_cvt_pk_bf16_f32 v28, v18, v19
	v_cvt_pk_bf16_f32 v29, v20, v21
	global_store_dwordx4 v[34:35], v[26:29], off offset:256

.LBB0_803:
	v_add_u32_e32 v0, 0xc00, v106
	s_nop 0
	v_add_u32_e32 v18, 48, v107
	v_cndmask_b32_e64 v28, v0, v18, s[10:11]
	v_ashrrev_i32_e32 v29, 31, v28
	v_lshlrev_b64 v[30:31], 11, v[28:29]
	v_lshl_add_u64 v[18:19], s[78:79], 0, v[30:31]
	v_cmp_gt_i32_e64 s[0:1], s73, v28
	s_and_b64 vcc, exec, s[14:15]
	v_lshl_add_u64 v[26:27], v[94:95], 1, v[18:19]
	s_cbranch_vccnz .LBB0_806
	s_waitcnt vmcnt(7)
	s_mov_b64 vcc, 0
	v_lshlrev_b32_e32 v22, 16, v134
	v_and_b32_e32 v23, 0xffff0000, v134
	v_lshlrev_b32_e32 v24, 16, v135
	v_and_b32_e32 v25, 0xffff0000, v135
	v_lshlrev_b32_e32 v18, 16, v136
	v_and_b32_e32 v19, 0xffff0000, v136
	v_lshlrev_b32_e32 v20, 16, v137
	v_and_b32_e32 v21, 0xffff0000, v137
	s_branch .LBB0_807

.LBB0_807:
	v_add_u32_e32 v0, 0xffffe000, v28
	v_readlane_b32 s36, v253, 24
	v_lshlrev_b64 v[34:35], 12, v[0:1]
	v_lshlrev_b64 v[32:33], 12, v[28:29]
	v_readlane_b32 s37, v253, 25
	v_readlane_b32 s38, v253, 26
	v_readlane_b32 s39, v253, 27
	v_lshl_add_u64 v[28:29], s[36:37], 0, v[32:33]
	s_andn2_b64 vcc, exec, vcc
	v_lshl_add_u64 v[34:35], s[38:39], 0, v[34:35]
	v_cndmask_b32_e64 v29, v35, v29, s[0:1]
	v_cndmask_b32_e64 v28, v34, v28, s[0:1]
	v_readlane_b32 s40, v253, 28
	v_readlane_b32 s41, v253, 29
	v_readlane_b32 s42, v253, 30
	v_readlane_b32 s43, v253, 31
	v_readlane_b32 s44, v253, 32
	v_readlane_b32 s45, v253, 33
	v_readlane_b32 s46, v253, 34
	v_readlane_b32 s47, v253, 35
	v_readlane_b32 s48, v253, 36
	v_readlane_b32 s49, v253, 37
	v_readlane_b32 s50, v253, 38
	v_readlane_b32 s51, v253, 39
	s_cbranch_vccnz .LBB0_809
	v_lshl_add_u64 v[22:23], v[94:95], 2, v[28:29]
	global_load_dwordx4 v[18:21], v[22:23], off offset:16
	s_nop 0
	global_load_dwordx4 v[22:25], v[22:23], off
	s_waitcnt vmcnt(0)
.LBB0_809:
	v_pk_fma_f32 v[10:11], v[10:11], v[54:55], v[18:19]
	v_lshl_add_u64 v[18:19], s[54:55], 0, v[30:31]
	v_pk_fma_f32 v[16:17], v[16:17], v[52:53], v[24:25]
	v_pk_fma_f32 v[14:15], v[14:15], v[50:51], v[22:23]
	v_pk_fma_f32 v[12:13], v[12:13], v[56:57], v[20:21]
	s_and_b64 vcc, exec, s[18:19]
	v_lshl_add_u64 v[18:19], v[94:95], 1, v[18:19]
	s_cbranch_vccnz .LBB0_811
	v_cvt_pk_bf16_f32 v20, v14, v15
	v_cvt_pk_bf16_f32 v21, v16, v17
	v_cvt_pk_bf16_f32 v22, v10, v11
	v_cvt_pk_bf16_f32 v23, v12, v13
	global_store_dwordx4 v[18:19], v[20:23], off

.LBB0_813:
	s_and_b64 vcc, exec, s[14:15]
	s_cbranch_vccnz .LBB0_823
	s_waitcnt vmcnt(7)
	v_lshlrev_b32_e32 v14, 16, v238
	v_and_b32_e32 v15, 0xffff0000, v238
	v_lshlrev_b32_e32 v16, 16, v239
	v_and_b32_e32 v17, 0xffff0000, v239
	v_lshlrev_b32_e32 v10, 16, v240
	v_and_b32_e32 v11, 0xffff0000, v240
	v_lshlrev_b32_e32 v12, 16, v241
	v_and_b32_e32 v13, 0xffff0000, v241
	s_cbranch_execnz .LBB0_816
.LBB0_815:
	v_lshl_add_u64 v[14:15], v[94:95], 2, v[28:29]
	global_load_dwordx4 v[10:13], v[14:15], off offset:528
	s_nop 0
	global_load_dwordx4 v[14:17], v[14:15], off offset:512
	s_waitcnt vmcnt(0)
.LBB0_816:
	v_pk_fma_f32 v[8:9], v[8:9], v[44:45], v[16:17]
	v_pk_fma_f32 v[6:7], v[6:7], v[42:43], v[14:15]
	v_pk_fma_f32 v[4:5], v[4:5], v[48:49], v[12:13]
	s_and_b64 vcc, exec, s[18:19]
	v_pk_fma_f32 v[2:3], v[2:3], v[46:47], v[10:11]
	s_cbranch_vccnz .LBB0_818
	v_cvt_pk_bf16_f32 v10, v6, v7
	v_cvt_pk_bf16_f32 v11, v8, v9
	v_cvt_pk_bf16_f32 v12, v2, v3
	v_cvt_pk_bf16_f32 v13, v4, v5
	global_store_dwordx4 v[18:19], v[10:13], off offset:256
